# sscan scalar-record loads hoisted + EpiB16 stores widened to dwordx4 via permlane16_swap (phase 4 and LoRA gemm)
# speedup vs baseline: 1.0196x; 1.0195x over previous
; __device__ __forceinline__ unsigned cvt_pk_bf16(float lo, float hi) { unsigned r; asm volatile("v_cvt_pk_bf16_f32 %0, %1, %2" : "=v"(r) : "v"(lo), "v"(hi)); return r; }
; #define PG8_BAR __builtin_amdgcn_s_barrier()
;     __device__ __forceinline__ void operator()(const f32x4 (&acc)[2][2][4][2], const Unit& u, int wr, int wc, int fr, int fq) const {
;         typedef unsigned u32x2 __attribute__((ext_vector_type(2)));
;         const int row0 = u.pm * BM + wr * 64 + fr, col0 = u.pn * BM + wc * 32 + 4 * fq;
; #pragma unroll
;         for (int ai = 0; ai < 2; ++ai)
; #pragma unroll
;             for (int m = 0; m < 4; ++m) {
;                 const size_t off = (size_t)(row0 + ai * HALF + m * 16) * ldc + col0;
; #pragma unroll
;                 for (int bj = 0; bj < 2; ++bj)
; #pragma unroll
;                     for (int n = 0; n < 2; ++n) { const f32x4 v = acc[ai][bj][m][n]; u32x2 w; w.x = cvt_pk_bf16(v[0], v[1]); w.y = cvt_pk_bf16(v[2], v[3]); *(u32x2*)(O + off + bj * HALF + n * 16) = w; }
;             }
; template <class Epi, class Sched, bool ALIGN_EPI = false, bool SP2 = false>
; __device__ __forceinline__ void gemm_phase(PG8_LAS unsigned char* lds, const Gemm g, const Sched& S, const Epi& E) {
;     ...
;         if constexpr (ALIGN_EPI) { if (wr == 1) PG8_BAR; }
.LBB0_460:
	v_lshl_or_b32 v148, s48, 8, v143
	v_lshl_add_u32 v147, s20, 8, v1
	v_ashrrev_i32_e32 v149, 31, v148
	v_cvt_pk_bf16_f32 v224, v126, v127
	v_mov_b64_e32 v[126:127], s[6:7]
	v_cvt_pk_bf16_f32 v225, v128, v129
	v_mad_i64_i32 v[152:153], s[22:23], v147, s43, v[126:127]
	v_lshlrev_b64 v[128:129], 1, v[148:149]
	v_and_b32_e32 v240, 16, v186
	v_lshrrev_b32_e32 v241, 1, v240
	v_add3_u32 v128, v128, v240, v241
	v_lshl_add_u64 v[148:149], v[152:153], 0, v[128:129]
	v_cvt_pk_bf16_f32 v226, v122, v123
	v_cvt_pk_bf16_f32 v227, v124, v125
	s_nop 1
	v_permlane16_swap_b32_e32 v224, v226
	v_permlane16_swap_b32_e32 v225, v227
	global_store_dwordx4 v[148:149], v[224:227], off
	v_cvt_pk_bf16_f32 v228, v114, v115
	v_cvt_pk_bf16_f32 v229, v116, v117
	v_cvt_pk_bf16_f32 v230, v106, v107
	v_cvt_pk_bf16_f32 v231, v108, v109
	v_or_b32_e32 v108, 16, v147
	v_mad_i64_i32 v[108:109], s[22:23], v108, s43, v[126:127]
	s_nop 1
	v_permlane16_swap_b32_e32 v228, v230
	v_permlane16_swap_b32_e32 v229, v231
	global_store_dwordx4 v[148:149], v[228:231], off offset:256
	v_cvt_pk_bf16_f32 v232, v118, v119
	v_cvt_pk_bf16_f32 v233, v120, v121
	v_lshl_add_u64 v[108:109], v[108:109], 0, v[128:129]
	v_cvt_pk_bf16_f32 v234, v110, v111
	v_cvt_pk_bf16_f32 v235, v112, v113
	s_nop 1
	v_permlane16_swap_b32_e32 v232, v234
	v_permlane16_swap_b32_e32 v233, v235
	global_store_dwordx4 v[108:109], v[232:235], off
	v_cvt_pk_bf16_f32 v236, v98, v99
	v_cvt_pk_bf16_f32 v237, v100, v101
	v_cvt_pk_bf16_f32 v238, v90, v91
	v_cvt_pk_bf16_f32 v239, v92, v93
	v_or_b32_e32 v92, 32, v147
	v_mad_i64_i32 v[92:93], s[22:23], v92, s43, v[126:127]
	s_nop 1
	v_permlane16_swap_b32_e32 v236, v238
	v_permlane16_swap_b32_e32 v237, v239
	global_store_dwordx4 v[108:109], v[236:239], off offset:256
	v_cvt_pk_bf16_f32 v224, v102, v103
	v_cvt_pk_bf16_f32 v225, v104, v105
	v_lshl_add_u64 v[92:93], v[92:93], 0, v[128:129]
	v_cvt_pk_bf16_f32 v226, v94, v95
	v_cvt_pk_bf16_f32 v227, v96, v97
	s_nop 1
	v_permlane16_swap_b32_e32 v224, v226
	v_permlane16_swap_b32_e32 v225, v227
	global_store_dwordx4 v[92:93], v[224:227], off
	v_cvt_pk_bf16_f32 v228, v82, v83
	v_cvt_pk_bf16_f32 v229, v84, v85
	v_cvt_pk_bf16_f32 v230, v74, v75
	v_cvt_pk_bf16_f32 v231, v76, v77
	v_or_b32_e32 v76, 48, v147
	v_mad_i64_i32 v[76:77], s[22:23], v76, s43, v[126:127]
	s_nop 1
	v_permlane16_swap_b32_e32 v228, v230
	v_permlane16_swap_b32_e32 v229, v231
	global_store_dwordx4 v[92:93], v[228:231], off offset:256
	v_cvt_pk_bf16_f32 v232, v86, v87
	v_cvt_pk_bf16_f32 v233, v88, v89
	v_lshl_add_u64 v[76:77], v[76:77], 0, v[128:129]
	v_cvt_pk_bf16_f32 v234, v78, v79
	v_cvt_pk_bf16_f32 v235, v80, v81
	s_nop 1
	v_permlane16_swap_b32_e32 v232, v234
	v_permlane16_swap_b32_e32 v233, v235
	global_store_dwordx4 v[76:77], v[232:235], off
	v_cvt_pk_bf16_f32 v236, v70, v71
	v_cvt_pk_bf16_f32 v237, v72, v73
	v_cvt_pk_bf16_f32 v238, v66, v67
	v_cvt_pk_bf16_f32 v239, v68, v69
	s_nop 1
	v_permlane16_swap_b32_e32 v236, v238
	v_permlane16_swap_b32_e32 v237, v239
	global_store_dwordx4 v[76:77], v[236:239], off offset:256
	v_add_u32_e32 v66, 0x80, v147
	v_cvt_pk_bf16_f32 v224, v62, v63
	v_cvt_pk_bf16_f32 v225, v64, v65
	v_mad_i64_i32 v[64:65], s[22:23], v66, s43, v[126:127]
	v_lshl_add_u64 v[64:65], v[64:65], 0, v[128:129]
	v_cvt_pk_bf16_f32 v226, v58, v59
	v_cvt_pk_bf16_f32 v227, v60, v61
	s_nop 1
	v_permlane16_swap_b32_e32 v224, v226
	v_permlane16_swap_b32_e32 v225, v227
	global_store_dwordx4 v[64:65], v[224:227], off
	v_cvt_pk_bf16_f32 v228, v50, v51
	v_cvt_pk_bf16_f32 v229, v52, v53
	v_cvt_pk_bf16_f32 v230, v42, v43
	v_cvt_pk_bf16_f32 v231, v44, v45
	v_add_u32_e32 v44, 0x90, v147
	v_mad_i64_i32 v[44:45], s[22:23], v44, s43, v[126:127]
	s_nop 1
	v_permlane16_swap_b32_e32 v228, v230
	v_permlane16_swap_b32_e32 v229, v231
	global_store_dwordx4 v[64:65], v[228:231], off offset:256
	v_cvt_pk_bf16_f32 v232, v54, v55
	v_cvt_pk_bf16_f32 v233, v56, v57
	v_lshl_add_u64 v[44:45], v[44:45], 0, v[128:129]
	v_cvt_pk_bf16_f32 v234, v46, v47
	v_cvt_pk_bf16_f32 v235, v48, v49
	s_nop 1
	v_permlane16_swap_b32_e32 v232, v234
	v_permlane16_swap_b32_e32 v233, v235
	global_store_dwordx4 v[44:45], v[232:235], off
	v_cvt_pk_bf16_f32 v236, v34, v35
	v_cvt_pk_bf16_f32 v237, v36, v37
	v_cvt_pk_bf16_f32 v238, v26, v27
	v_cvt_pk_bf16_f32 v239, v28, v29
	v_add_u32_e32 v28, 0xa0, v147
	v_mad_i64_i32 v[28:29], s[22:23], v28, s43, v[126:127]
	s_nop 1
	v_permlane16_swap_b32_e32 v236, v238
	v_permlane16_swap_b32_e32 v237, v239
	global_store_dwordx4 v[44:45], v[236:239], off offset:256
	v_cvt_pk_bf16_f32 v224, v38, v39
	v_cvt_pk_bf16_f32 v225, v40, v41
	v_lshl_add_u64 v[28:29], v[28:29], 0, v[128:129]
	v_cvt_pk_bf16_f32 v226, v30, v31
	v_cvt_pk_bf16_f32 v227, v32, v33
	s_nop 1
	v_permlane16_swap_b32_e32 v224, v226
	v_permlane16_swap_b32_e32 v225, v227
	global_store_dwordx4 v[28:29], v[224:227], off
	v_cvt_pk_bf16_f32 v228, v18, v19
	v_cvt_pk_bf16_f32 v229, v20, v21
	v_cvt_pk_bf16_f32 v230, v10, v11
	v_cvt_pk_bf16_f32 v231, v12, v13
	v_add_u32_e32 v12, 0xb0, v147
	v_mad_i64_i32 v[12:13], s[22:23], v12, s43, v[126:127]
	s_nop 1
	v_permlane16_swap_b32_e32 v228, v230
	v_permlane16_swap_b32_e32 v229, v231
	global_store_dwordx4 v[28:29], v[228:231], off offset:256
	v_cvt_pk_bf16_f32 v232, v22, v23
	v_cvt_pk_bf16_f32 v233, v24, v25
	v_lshl_add_u64 v[12:13], v[12:13], 0, v[128:129]
	s_andn2_b64 vcc, exec, s[2:3]
	s_mov_b64 s[2:3], -1
	v_cvt_pk_bf16_f32 v234, v14, v15
	v_cvt_pk_bf16_f32 v235, v16, v17
	s_nop 1
	v_permlane16_swap_b32_e32 v232, v234
	v_permlane16_swap_b32_e32 v233, v235
	global_store_dwordx4 v[12:13], v[232:235], off
	v_cvt_pk_bf16_f32 v236, v6, v7
	v_cvt_pk_bf16_f32 v237, v8, v9
	v_cvt_pk_bf16_f32 v238, v2, v3
	v_cvt_pk_bf16_f32 v239, v4, v5
	s_nop 1
	v_permlane16_swap_b32_e32 v236, v238
	v_permlane16_swap_b32_e32 v237, v239
	global_store_dwordx4 v[12:13], v[236:239], off offset:256
	s_cbranch_vccnz .LBB0_449
	s_andn2_b64 vcc, exec, s[4:5]
	s_cbranch_vccnz .LBB0_448
	s_barrier
	s_branch .LBB0_448

; __device__ __forceinline__ unsigned cvt_pk_bf16(float lo, float hi) { unsigned r; asm volatile("v_cvt_pk_bf16_f32 %0, %1, %2" : "=v"(r) : "v"(lo), "v"(hi)); return r; }
;     __device__ __forceinline__ void operator()(const f32x4 (&acc)[2][2][4][2], const Unit& u, int wr, int wc, int fr, int fq) const {
;         typedef unsigned u32x2 __attribute__((ext_vector_type(2)));
;         const int row0 = u.pm * BM + wr * 64 + fr, col0 = u.pn * BM + wc * 32 + 4 * fq;
; #pragma unroll
;         for (int ai = 0; ai < 2; ++ai)
; #pragma unroll
;             for (int m = 0; m < 4; ++m) {
;                 const size_t off = (size_t)(row0 + ai * HALF + m * 16) * ldc + col0;
; #pragma unroll
;                 for (int bj = 0; bj < 2; ++bj)
; #pragma unroll
;                     for (int n = 0; n < 2; ++n) { const f32x4 v = acc[ai][bj][m][n]; u32x2 w; w.x = cvt_pk_bf16(v[0], v[1]); w.y = cvt_pk_bf16(v[2], v[3]); *(u32x2*)(O + off + bj * HALF + n * 16) = w; }
;             }
.LBB0_794:
	v_lshl_or_b32 v148, s52, 8, v143
	v_lshl_add_u32 v147, s53, 8, v1
	v_ashrrev_i32_e32 v149, 31, v148
	v_cvt_pk_bf16_f32 v228, v126, v127
	v_cvt_pk_bf16_f32 v229, v128, v129
	v_mov_b64_e32 v[128:129], s[14:15]
	v_mad_i64_i32 v[150:151], s[22:23], v147, s49, v[128:129]
	v_lshlrev_b64 v[148:149], 1, v[148:149]
	v_and_b32_e32 v244, 16, v186
	v_lshrrev_b32_e32 v245, 1, v244
	v_add3_u32 v148, v148, v244, v245
	v_lshl_add_u64 v[150:151], v[150:151], 0, v[148:149]
	v_cvt_pk_bf16_f32 v230, v122, v123
	v_cvt_pk_bf16_f32 v231, v124, v125
	s_nop 1
	v_permlane16_swap_b32_e32 v228, v230
	v_permlane16_swap_b32_e32 v229, v231
	global_store_dwordx4 v[150:151], v[228:231], off
	v_cvt_pk_bf16_f32 v232, v118, v119
	v_cvt_pk_bf16_f32 v233, v120, v121
	v_cvt_pk_bf16_f32 v234, v114, v115
	v_cvt_pk_bf16_f32 v235, v116, v117
	s_nop 1
	v_permlane16_swap_b32_e32 v232, v234
	v_permlane16_swap_b32_e32 v233, v235
	global_store_dwordx4 v[150:151], v[232:235], off offset:256
	v_or_b32_e32 v114, 16, v147
	v_cvt_pk_bf16_f32 v236, v110, v111
	v_cvt_pk_bf16_f32 v237, v112, v113
	v_mad_i64_i32 v[112:113], s[22:23], v114, s49, v[128:129]
	v_lshl_add_u64 v[112:113], v[112:113], 0, v[148:149]
	v_cvt_pk_bf16_f32 v238, v106, v107
	v_cvt_pk_bf16_f32 v239, v108, v109
	s_nop 1
	v_permlane16_swap_b32_e32 v236, v238
	v_permlane16_swap_b32_e32 v237, v239
	global_store_dwordx4 v[112:113], v[236:239], off
	v_cvt_pk_bf16_f32 v240, v102, v103
	v_cvt_pk_bf16_f32 v241, v104, v105
	v_cvt_pk_bf16_f32 v242, v98, v99
	v_cvt_pk_bf16_f32 v243, v100, v101
	s_nop 1
	v_permlane16_swap_b32_e32 v240, v242
	v_permlane16_swap_b32_e32 v241, v243
	global_store_dwordx4 v[112:113], v[240:243], off offset:256
	v_or_b32_e32 v98, 32, v147
	v_cvt_pk_bf16_f32 v228, v94, v95
	v_cvt_pk_bf16_f32 v229, v96, v97
	v_mad_i64_i32 v[96:97], s[22:23], v98, s49, v[128:129]
	v_lshl_add_u64 v[96:97], v[96:97], 0, v[148:149]
	v_cvt_pk_bf16_f32 v230, v90, v91
	v_cvt_pk_bf16_f32 v231, v92, v93
	s_nop 1
	v_permlane16_swap_b32_e32 v228, v230
	v_permlane16_swap_b32_e32 v229, v231
	global_store_dwordx4 v[96:97], v[228:231], off
	v_cvt_pk_bf16_f32 v232, v86, v87
	v_cvt_pk_bf16_f32 v233, v88, v89
	v_cvt_pk_bf16_f32 v234, v82, v83
	v_cvt_pk_bf16_f32 v235, v84, v85
	s_nop 1
	v_permlane16_swap_b32_e32 v232, v234
	v_permlane16_swap_b32_e32 v233, v235
	global_store_dwordx4 v[96:97], v[232:235], off offset:256
	v_or_b32_e32 v82, 48, v147
	v_cvt_pk_bf16_f32 v236, v78, v79
	v_cvt_pk_bf16_f32 v237, v80, v81
	v_mad_i64_i32 v[80:81], s[22:23], v82, s49, v[128:129]
	v_lshl_add_u64 v[80:81], v[80:81], 0, v[148:149]
	v_cvt_pk_bf16_f32 v238, v74, v75
	v_cvt_pk_bf16_f32 v239, v76, v77
	s_nop 1
	v_permlane16_swap_b32_e32 v236, v238
	v_permlane16_swap_b32_e32 v237, v239
	global_store_dwordx4 v[80:81], v[236:239], off
	v_cvt_pk_bf16_f32 v240, v70, v71
	v_cvt_pk_bf16_f32 v241, v72, v73
	v_cvt_pk_bf16_f32 v242, v66, v67
	v_cvt_pk_bf16_f32 v243, v68, v69
	s_nop 1
	v_permlane16_swap_b32_e32 v240, v242
	v_permlane16_swap_b32_e32 v241, v243
	global_store_dwordx4 v[80:81], v[240:243], off offset:256
	v_add_u32_e32 v66, 0x80, v147
	v_cvt_pk_bf16_f32 v228, v62, v63
	v_cvt_pk_bf16_f32 v229, v64, v65
	v_mad_i64_i32 v[64:65], s[22:23], v66, s49, v[128:129]
	v_lshl_add_u64 v[64:65], v[64:65], 0, v[148:149]
	v_cvt_pk_bf16_f32 v230, v58, v59
	v_cvt_pk_bf16_f32 v231, v60, v61
	s_nop 1
	v_permlane16_swap_b32_e32 v228, v230
	v_permlane16_swap_b32_e32 v229, v231
	global_store_dwordx4 v[64:65], v[228:231], off
	v_cvt_pk_bf16_f32 v232, v54, v55
	v_cvt_pk_bf16_f32 v233, v56, v57
	v_cvt_pk_bf16_f32 v234, v50, v51
	v_cvt_pk_bf16_f32 v235, v52, v53
	s_nop 1
	v_permlane16_swap_b32_e32 v232, v234
	v_permlane16_swap_b32_e32 v233, v235
	global_store_dwordx4 v[64:65], v[232:235], off offset:256
	v_add_u32_e32 v50, 0x90, v147
	v_cvt_pk_bf16_f32 v236, v46, v47
	v_cvt_pk_bf16_f32 v237, v48, v49
	v_mad_i64_i32 v[48:49], s[22:23], v50, s49, v[128:129]
	v_lshl_add_u64 v[48:49], v[48:49], 0, v[148:149]
	v_cvt_pk_bf16_f32 v238, v42, v43
	v_cvt_pk_bf16_f32 v239, v44, v45
	s_nop 1
	v_permlane16_swap_b32_e32 v236, v238
	v_permlane16_swap_b32_e32 v237, v239
	global_store_dwordx4 v[48:49], v[236:239], off
	v_cvt_pk_bf16_f32 v240, v38, v39
	v_cvt_pk_bf16_f32 v241, v40, v41
	v_cvt_pk_bf16_f32 v242, v34, v35
	v_cvt_pk_bf16_f32 v243, v36, v37
	s_nop 1
	v_permlane16_swap_b32_e32 v240, v242
	v_permlane16_swap_b32_e32 v241, v243
	global_store_dwordx4 v[48:49], v[240:243], off offset:256
	v_add_u32_e32 v34, 0xa0, v147
	v_cvt_pk_bf16_f32 v228, v30, v31
	v_cvt_pk_bf16_f32 v229, v32, v33
	v_mad_i64_i32 v[32:33], s[22:23], v34, s49, v[128:129]
	v_lshl_add_u64 v[32:33], v[32:33], 0, v[148:149]
	v_cvt_pk_bf16_f32 v230, v26, v27
	v_cvt_pk_bf16_f32 v231, v28, v29
	s_nop 1
	v_permlane16_swap_b32_e32 v228, v230
	v_permlane16_swap_b32_e32 v229, v231
	global_store_dwordx4 v[32:33], v[228:231], off
	v_cvt_pk_bf16_f32 v232, v22, v23
	v_cvt_pk_bf16_f32 v233, v24, v25
	v_cvt_pk_bf16_f32 v234, v18, v19
	v_cvt_pk_bf16_f32 v235, v20, v21
	s_nop 1
	v_permlane16_swap_b32_e32 v232, v234
	v_permlane16_swap_b32_e32 v233, v235
	global_store_dwordx4 v[32:33], v[232:235], off offset:256
	v_add_u32_e32 v18, 0xb0, v147
	v_cvt_pk_bf16_f32 v236, v14, v15
	v_cvt_pk_bf16_f32 v237, v16, v17
	v_mad_i64_i32 v[16:17], s[22:23], v18, s49, v[128:129]
	v_lshl_add_u64 v[16:17], v[16:17], 0, v[148:149]
	s_and_b64 vcc, exec, s[2:3]
	s_mov_b64 s[2:3], -1
	v_cvt_pk_bf16_f32 v238, v10, v11
	v_cvt_pk_bf16_f32 v239, v12, v13
	s_nop 1
	v_permlane16_swap_b32_e32 v236, v238
	v_permlane16_swap_b32_e32 v237, v239
	global_store_dwordx4 v[16:17], v[236:239], off
	v_cvt_pk_bf16_f32 v240, v6, v7
	v_cvt_pk_bf16_f32 v241, v8, v9
	v_cvt_pk_bf16_f32 v242, v2, v3
	v_cvt_pk_bf16_f32 v243, v4, v5
	s_nop 1
	v_permlane16_swap_b32_e32 v240, v242
	v_permlane16_swap_b32_e32 v241, v243
	global_store_dwordx4 v[16:17], v[240:243], off offset:256
	s_cbranch_vccnz .LBB0_782
	s_andn2_b64 vcc, exec, s[12:13]
	s_cbranch_vccnz .LBB0_781
	s_barrier
	s_branch .LBB0_781

; #define GAS __attribute__((address_space(1)))
; DI float dot4(const f32x4& x, const f32x4& y) { return fmaf(x.y, y.y, x.x * y.x) + fmaf(x.w, y.w, x.z * y.z); }
; DI void sscan_wave(const float* SC5, const float* RKV, const float* SCAL, float* Y, const float* init, float* fin, int chain, int rg, int lane) {
;     ...
; #pragma unroll
;     for (int t = 0; t < DS; ++t) {
;         const size_t m = (size_t)MP + (size_t)b * DS + t; const float* p5 = SC5 + m * RWD + hd * 64 + 4 * j;
;         const f32x4 a4 = *(const GAS f32x4*)p5, wr4 = *(const GAS f32x4*)(p5 + ASZ), w4 = *(const GAS f32x4*)(p5 + 2 * ASZ), b4 = *(const GAS f32x4*)(p5 + 3 * ASZ), k4 = *(const GAS f32x4*)(p5 + 4 * ASZ);
;         const float vv = ((const GAS float*)RKV)[m * 1536 + 1024 + hd * 64 + row]; const f32x2 sc = *(const GAS f32x2*)(SCAL + (m * 8 + hd) * 4);
;         const float sa = rowsum16(dot4(s, a4)), y1 = rowsum16(dot4(s, wr4));
;         s = s * w4 + b4 * sa + k4 * vv;
;         if (j == 0) ((GAS float*)Y)[m * RWD + hd * 64 + row] = y1 + 16.f * (sa * sc.x + vv * sc.y);
;     }
;     *(GAS f32x4*)(fin + (size_t)chain * 4096 + (size_t)row * 64 + 4 * j) = s;
.LBB0_1218:
	s_ashr_i32 s4, s16, 3
	s_ashr_i32 s17, s16, 31
	s_lshl_b64 s[18:19], s[16:17], 14
	s_ashr_i32 s5, s4, 31
	s_and_b32 s36, s16, 7
	v_lshl_add_u64 v[2:3], v[34:35], 0, s[18:19]
	s_lshl_b64 s[18:19], s[4:5], 3
	s_add_u32 s20, s18, 0x8000
	s_addc_u32 s21, s19, 0
	s_lshl_b32 s12, s36, 8
	s_lshl_b32 s4, s36, 4
	s_add_u32 s15, s74, s4
	v_lshl_add_u64 v[44:45], v[32:33], 0, s[12:13]
	s_addc_u32 s35, s75, 0
	s_lshl_b64 s[4:5], s[20:21], 11
	v_lshl_add_u64 v[18:19], v[44:45], 0, s[4:5]
	v_add_co_u32_e64 v10, s[4:5], s25, v18
	global_load_dwordx4 v[2:5], v[2:3], off
	s_nop 0
	v_addc_co_u32_e64 v11, s[4:5], 0, v19, s[4:5]
	global_load_dwordx4 v[6:9], v[18:19], off
	global_load_dwordx4 v[14:17], v[10:11], off
	v_add_co_u32_e64 v10, s[4:5], s26, v18
	v_lshl_add_u64 v[42:43], v[36:37], 0, s[12:13]
	s_nop 0
	v_addc_co_u32_e64 v11, s[4:5], 0, v19, s[4:5]
	v_add_co_u32_e64 v20, s[4:5], s27, v18
	s_nop 1
	v_addc_co_u32_e64 v21, s[4:5], 0, v19, s[4:5]
	v_add_co_u32_e64 v18, s[4:5], s28, v18
	global_load_dwordx4 v[10:13], v[10:11], off
	s_nop 0
	global_load_dwordx4 v[26:29], v[20:21], off
	v_addc_co_u32_e64 v19, s[4:5], 0, v19, s[4:5]
	s_mul_i32 s4, s21, 0x1800
	s_mul_hi_u32 s5, s20, 0x1800
	s_add_i32 s5, s5, s4
	s_mul_i32 s4, s20, 0x1800
	s_add_u32 s37, s0, s4
	s_addc_u32 s38, s1, s5
	s_add_u32 s4, s37, s12
	s_addc_u32 s5, s38, 0
	v_lshl_add_u64 v[20:21], s[4:5], 0, v[30:31]
	v_add_co_u32_e64 v20, s[4:5], s29, v20
	s_nop 1
	v_addc_co_u32_e64 v21, s[4:5], 0, v21, s[4:5]
	global_load_dwordx4 v[22:25], v[18:19], off
	global_load_dword v46, v[20:21], off
	s_lshl_b64 s[98:99], s[20:21], 7
	s_add_u32 s98, s15, s98
	s_addc_u32 s99, s35, s99
	global_load_dwordx2 v[64:65], v31, s[98:99]
	s_waitcnt vmcnt(6)
	v_mov_b32_e32 v18, v3
	v_mov_b32_e32 v19, v5
	s_waitcnt vmcnt(5)
	v_mul_f32_e32 v20, v2, v6
	v_mul_f32_e32 v21, v4, v8
	v_mov_b32_e32 v8, v7
	v_pk_fma_f32 v[6:7], v[18:19], v[8:9], v[20:21]
	s_waitcnt vmcnt(4)
	v_mul_f32_e32 v8, v2, v14
	v_mul_f32_e32 v9, v4, v16
	v_add_f32_e32 v6, v6, v7
	v_fmac_f32_e32 v8, v3, v15
	v_fmac_f32_e32 v9, v5, v17
	v_add_f32_dpp v6, v6, v6 row_ror:8 row_mask:0xf bank_mask:0xf bound_ctrl:1
	v_add_f32_e32 v7, v8, v9
	v_mov_b32_e32 v8, 0
	v_add_f32_dpp v6, v6, v6 row_ror:4 row_mask:0xf bank_mask:0xf bound_ctrl:1
	v_add_f32_dpp v7, v7, v7 row_ror:8 row_mask:0xf bank_mask:0xf bound_ctrl:1
	s_nop 0
	v_add_f32_dpp v6, v6, v6 row_ror:2 row_mask:0xf bank_mask:0xf bound_ctrl:1
	v_add_f32_dpp v7, v7, v7 row_ror:4 row_mask:0xf bank_mask:0xf bound_ctrl:1
	s_nop 0
	v_add_f32_dpp v50, v6, v6 row_ror:1 row_mask:0xf bank_mask:0xf bound_ctrl:1
	v_add_f32_dpp v6, v7, v7 row_ror:2 row_mask:0xf bank_mask:0xf bound_ctrl:1
	s_nop 1
	v_mov_b32_dpp v8, v6 row_ror:1 row_mask:0xf bank_mask:0xf
	s_and_saveexec_b64 s[4:5], vcc
	s_cbranch_execz .LBB0_1220
	s_lshl_b64 s[40:41], s[20:21], 9
	v_lshl_add_u64 v[16:17], s[40:41], 2, v[42:43]
	s_waitcnt vmcnt(0)
	v_mul_f32_e32 v7, v50, v64
	v_mul_f32_e32 v9, v46, v65
	v_pk_add_f32 v[6:7], v[6:7], v[8:9]
	s_nop 0
	v_fmac_f32_e32 v6, 0x41800000, v7
	global_store_dword v[16:17], v6, off
.LBB0_1220:
	s_or_b64 exec, exec, s[4:5]
	s_lshl_b32 s12, s36, 6
	s_add_u32 s20, s18, 0x8001
	s_addc_u32 s21, s19, 0
	s_lshl_b64 s[4:5], s[20:21], 11
	v_lshl_add_u64 v[14:15], v[44:45], 0, s[4:5]
	v_add_co_u32_e64 v6, s[4:5], s25, v14
	s_add_u32 s36, s37, 0x1800
	s_nop 0
	v_addc_co_u32_e64 v7, s[4:5], 0, v15, s[4:5]
	global_load_dwordx4 v[54:57], v[14:15], off
	global_load_dwordx4 v[58:61], v[6:7], off
	v_add_co_u32_e64 v6, s[4:5], s26, v14
	s_addc_u32 s37, s38, 0
	s_nop 0
	v_addc_co_u32_e64 v7, s[4:5], 0, v15, s[4:5]
	v_add_co_u32_e64 v16, s[4:5], s27, v14
	s_lshl_b32 s12, s12, 2
	s_nop 0
	v_addc_co_u32_e64 v17, s[4:5], 0, v15, s[4:5]
	v_add_co_u32_e64 v14, s[4:5], s28, v14
	global_load_dwordx4 v[6:9], v[6:7], off
	s_nop 0
	global_load_dwordx4 v[18:21], v[16:17], off
	v_addc_co_u32_e64 v15, s[4:5], 0, v15, s[4:5]
	s_add_u32 s4, s36, s12
	s_addc_u32 s5, s37, 0
	v_lshl_add_u64 v[16:17], s[4:5], 0, v[30:31]
	v_add_co_u32_e64 v48, s[4:5], s29, v16
	s_waitcnt vmcnt(6)
	v_pk_mul_f32 v[28:29], v[28:29], v[50:51] op_sel_hi:[1,0]
	v_addc_co_u32_e64 v49, s[4:5], 0, v17, s[4:5]
	global_load_dwordx4 v[14:17], v[14:15], off
	s_nop 0
	global_load_dword v48, v[48:49], off
	s_lshl_b64 s[98:99], s[20:21], 7
	s_add_u32 s98, s15, s98
	s_addc_u32 s99, s35, s99
	global_load_dwordx2 v[64:65], v31, s[98:99]
	v_pk_mul_f32 v[26:27], v[26:27], v[50:51] op_sel_hi:[1,0]
	v_pk_fma_f32 v[4:5], v[4:5], v[12:13], v[28:29]
	v_pk_fma_f32 v[2:3], v[2:3], v[10:11], v[26:27]
	s_waitcnt vmcnt(6)
	v_pk_fma_f32 v[26:27], v[24:25], v[46:47], v[4:5] op_sel_hi:[1,0,1]
	v_pk_fma_f32 v[28:29], v[22:23], v[46:47], v[2:3] op_sel_hi:[1,0,1]
	v_mov_b32_e32 v3, v27
	v_mov_b32_e32 v2, v29
	v_mov_b32_e32 v52, v31
	s_waitcnt vmcnt(5)
	v_pk_mul_f32 v[4:5], v[28:29], v[54:55]
	v_pk_mul_f32 v[10:11], v[26:27], v[56:57]
	v_mov_b32_e32 v56, v55
	v_mov_b32_e32 v5, v10
	s_waitcnt vmcnt(4)
	v_mul_f32_e32 v10, v28, v58
	v_mul_f32_e32 v11, v26, v60
	v_pk_fma_f32 v[2:3], v[2:3], v[56:57], v[4:5]
	v_fmac_f32_e32 v10, v29, v59
	v_fmac_f32_e32 v11, v27, v61
	v_add_f32_e32 v2, v2, v3
	v_add_f32_e32 v3, v10, v11
	s_nop 0
	v_add_f32_dpp v2, v2, v2 row_ror:8 row_mask:0xf bank_mask:0xf bound_ctrl:1
	v_add_f32_dpp v3, v3, v3 row_ror:8 row_mask:0xf bank_mask:0xf bound_ctrl:1
	s_nop 0
	v_add_f32_dpp v2, v2, v2 row_ror:4 row_mask:0xf bank_mask:0xf bound_ctrl:1
	v_add_f32_dpp v3, v3, v3 row_ror:4 row_mask:0xf bank_mask:0xf bound_ctrl:1
	s_nop 0
	v_add_f32_dpp v4, v2, v2 row_ror:2 row_mask:0xf bank_mask:0xf bound_ctrl:1
	v_add_f32_dpp v2, v3, v3 row_ror:2 row_mask:0xf bank_mask:0xf bound_ctrl:1
	s_nop 0
	v_add_f32_dpp v50, v4, v4 row_ror:1 row_mask:0xf bank_mask:0xf bound_ctrl:1
	v_mov_b32_dpp v52, v2 row_ror:1 row_mask:0xf bank_mask:0xf
	s_and_saveexec_b64 s[4:5], vcc
	s_cbranch_execz .LBB0_1222
	s_lshl_b64 s[38:39], s[20:21], 9
	v_lshl_add_u64 v[10:11], s[38:39], 2, v[42:43]
	s_waitcnt vmcnt(0)
	v_mul_f32_e32 v3, v50, v64
	v_mul_f32_e32 v53, v48, v65
	v_pk_add_f32 v[2:3], v[2:3], v[52:53]
	s_nop 0
	v_fmac_f32_e32 v2, 0x41800000, v3
	global_store_dword v[10:11], v2, off
; #define GAS __attribute__((address_space(1)))
; DI float dot4(const f32x4& x, const f32x4& y) { return fmaf(x.y, y.y, x.x * y.x) + fmaf(x.w, y.w, x.z * y.z); }
; DI void sscan_wave(const float* SC5, const float* RKV, const float* SCAL, float* Y, const float* init, float* fin, int chain, int rg, int lane) {
;     ...
; #pragma unroll
;     for (int t = 0; t < DS; ++t) {
;         const size_t m = (size_t)MP + (size_t)b * DS + t; const float* p5 = SC5 + m * RWD + hd * 64 + 4 * j;
;         const f32x4 a4 = *(const GAS f32x4*)p5, wr4 = *(const GAS f32x4*)(p5 + ASZ), w4 = *(const GAS f32x4*)(p5 + 2 * ASZ), b4 = *(const GAS f32x4*)(p5 + 3 * ASZ), k4 = *(const GAS f32x4*)(p5 + 4 * ASZ);
;         const float vv = ((const GAS float*)RKV)[m * 1536 + 1024 + hd * 64 + row]; const f32x2 sc = *(const GAS f32x2*)(SCAL + (m * 8 + hd) * 4);
;         const float sa = rowsum16(dot4(s, a4)), y1 = rowsum16(dot4(s, wr4));
;         s = s * w4 + b4 * sa + k4 * vv;
;         if (j == 0) ((GAS float*)Y)[m * RWD + hd * 64 + row] = y1 + 16.f * (sa * sc.x + vv * sc.y);
;     }
;     *(GAS f32x4*)(fin + (size_t)chain * 4096 + (size_t)row * 64 + 4 * j) = s;
.LBB0_1222:
	s_or_b64 exec, exec, s[4:5]
	s_add_u32 s20, s18, 0x8002
	s_addc_u32 s21, s19, 0
	s_lshl_b64 s[4:5], s[20:21], 11
	v_lshl_add_u64 v[10:11], v[44:45], 0, s[4:5]
	v_add_co_u32_e64 v2, s[4:5], s25, v10
	s_add_u32 s36, s36, 0x1800
	s_nop 0
	v_addc_co_u32_e64 v3, s[4:5], 0, v11, s[4:5]
	global_load_dwordx4 v[52:55], v[10:11], off
	global_load_dwordx4 v[56:59], v[2:3], off
	v_add_co_u32_e64 v2, s[4:5], s26, v10
	s_addc_u32 s37, s37, 0
	s_nop 0
	v_addc_co_u32_e64 v3, s[4:5], 0, v11, s[4:5]
	v_add_co_u32_e64 v12, s[4:5], s27, v10
	s_waitcnt vmcnt(4)
	v_pk_mul_f32 v[20:21], v[20:21], v[50:51] op_sel_hi:[1,0]
	v_addc_co_u32_e64 v13, s[4:5], 0, v11, s[4:5]
	v_add_co_u32_e64 v10, s[4:5], s28, v10
	global_load_dwordx4 v[2:5], v[2:3], off
	s_nop 0
	global_load_dwordx4 v[22:25], v[12:13], off
	v_addc_co_u32_e64 v11, s[4:5], 0, v11, s[4:5]
	s_add_u32 s4, s36, s12
	s_addc_u32 s5, s37, 0
	v_lshl_add_u64 v[12:13], s[4:5], 0, v[30:31]
	v_add_co_u32_e64 v46, s[4:5], s29, v12
	v_pk_mul_f32 v[50:51], v[18:19], v[50:51] op_sel_hi:[1,0]
	s_nop 0
	v_addc_co_u32_e64 v47, s[4:5], 0, v13, s[4:5]
	global_load_dwordx4 v[10:13], v[10:11], off
	s_nop 0
	global_load_dword v46, v[46:47], off
	s_lshl_b64 s[98:99], s[20:21], 7
	s_add_u32 s98, s15, s98
	s_addc_u32 s99, s35, s99
	global_load_dwordx2 v[64:65], v31, s[98:99]
	v_pk_fma_f32 v[8:9], v[26:27], v[8:9], v[20:21]
	v_pk_fma_f32 v[6:7], v[28:29], v[6:7], v[50:51]
	s_waitcnt vmcnt(6)
	v_pk_fma_f32 v[16:17], v[16:17], v[48:49], v[8:9] op_sel_hi:[1,0,1]
	v_pk_fma_f32 v[14:15], v[14:15], v[48:49], v[6:7] op_sel_hi:[1,0,1]
	v_mov_b32_e32 v7, v17
	v_mov_b32_e32 v6, v15
	v_mov_b32_e32 v18, v31
	s_waitcnt vmcnt(5)
	v_pk_mul_f32 v[8:9], v[14:15], v[52:53]
	v_pk_mul_f32 v[20:21], v[16:17], v[54:55]
	v_mov_b32_e32 v54, v53
	v_mov_b32_e32 v9, v20
	s_waitcnt vmcnt(4)
	v_mul_f32_e32 v19, v14, v56
	v_mul_f32_e32 v20, v16, v58
	v_pk_fma_f32 v[6:7], v[6:7], v[54:55], v[8:9]
	v_fmac_f32_e32 v19, v15, v57
	v_fmac_f32_e32 v20, v17, v59
	v_add_f32_e32 v6, v6, v7
	v_add_f32_e32 v7, v19, v20
	s_nop 0
	v_add_f32_dpp v6, v6, v6 row_ror:8 row_mask:0xf bank_mask:0xf bound_ctrl:1
	v_add_f32_dpp v7, v7, v7 row_ror:8 row_mask:0xf bank_mask:0xf bound_ctrl:1
	s_nop 0
	v_add_f32_dpp v6, v6, v6 row_ror:4 row_mask:0xf bank_mask:0xf bound_ctrl:1
	v_add_f32_dpp v7, v7, v7 row_ror:4 row_mask:0xf bank_mask:0xf bound_ctrl:1
	s_nop 0
	v_add_f32_dpp v8, v6, v6 row_ror:2 row_mask:0xf bank_mask:0xf bound_ctrl:1
	v_add_f32_dpp v6, v7, v7 row_ror:2 row_mask:0xf bank_mask:0xf bound_ctrl:1
	s_nop 0
	v_add_f32_dpp v50, v8, v8 row_ror:1 row_mask:0xf bank_mask:0xf bound_ctrl:1
	v_mov_b32_dpp v18, v6 row_ror:1 row_mask:0xf bank_mask:0xf
	s_and_saveexec_b64 s[4:5], vcc
	s_cbranch_execz .LBB0_1224
	s_lshl_b64 s[38:39], s[20:21], 9
	v_lshl_add_u64 v[20:21], s[38:39], 2, v[42:43]
	s_waitcnt vmcnt(0)
	v_mul_f32_e32 v7, v50, v64
	v_mul_f32_e32 v19, v46, v65
	v_pk_add_f32 v[6:7], v[6:7], v[18:19]
	s_nop 0
	v_fmac_f32_e32 v6, 0x41800000, v7
	global_store_dword v[20:21], v6, off
.LBB0_1224:
	s_or_b64 exec, exec, s[4:5]
	s_add_u32 s20, s18, 0x8003
	s_addc_u32 s21, s19, 0
	s_lshl_b64 s[4:5], s[20:21], 11
	v_lshl_add_u64 v[18:19], v[44:45], 0, s[4:5]
	v_add_co_u32_e64 v6, s[4:5], s25, v18
	s_add_u32 s36, s36, 0x1800
	s_nop 0
	v_addc_co_u32_e64 v7, s[4:5], 0, v19, s[4:5]
	global_load_dwordx4 v[52:55], v[18:19], off
	global_load_dwordx4 v[56:59], v[6:7], off
	v_add_co_u32_e64 v6, s[4:5], s26, v18
	s_addc_u32 s37, s37, 0
	s_nop 0
	v_addc_co_u32_e64 v7, s[4:5], 0, v19, s[4:5]
	v_add_co_u32_e64 v20, s[4:5], s27, v18
	s_waitcnt vmcnt(4)
	v_pk_mul_f32 v[24:25], v[24:25], v[50:51] op_sel_hi:[1,0]
	v_addc_co_u32_e64 v21, s[4:5], 0, v19, s[4:5]
	v_add_co_u32_e64 v18, s[4:5], s28, v18
	global_load_dwordx4 v[6:9], v[6:7], off
	s_nop 0
	global_load_dwordx4 v[26:29], v[20:21], off
	v_addc_co_u32_e64 v19, s[4:5], 0, v19, s[4:5]
	s_add_u32 s4, s36, s12
	s_addc_u32 s5, s37, 0
	v_lshl_add_u64 v[20:21], s[4:5], 0, v[30:31]
	v_add_co_u32_e64 v48, s[4:5], s29, v20
	v_pk_mul_f32 v[50:51], v[22:23], v[50:51] op_sel_hi:[1,0]
	s_nop 0
	v_addc_co_u32_e64 v49, s[4:5], 0, v21, s[4:5]
	global_load_dwordx4 v[18:21], v[18:19], off
	s_nop 0
	global_load_dword v48, v[48:49], off
	s_lshl_b64 s[98:99], s[20:21], 7
	s_add_u32 s98, s15, s98
	s_addc_u32 s99, s35, s99
	global_load_dwordx2 v[64:65], v31, s[98:99]
	v_pk_fma_f32 v[4:5], v[16:17], v[4:5], v[24:25]
	v_pk_fma_f32 v[2:3], v[14:15], v[2:3], v[50:51]
	s_waitcnt vmcnt(6)
	v_pk_fma_f32 v[12:13], v[12:13], v[46:47], v[4:5] op_sel_hi:[1,0,1]
	v_pk_fma_f32 v[10:11], v[10:11], v[46:47], v[2:3] op_sel_hi:[1,0,1]
	v_mov_b32_e32 v3, v13
	v_mov_b32_e32 v2, v11
	v_mov_b32_e32 v22, v31
	s_waitcnt vmcnt(5)
	v_pk_mul_f32 v[4:5], v[10:11], v[52:53]
	v_pk_mul_f32 v[14:15], v[12:13], v[54:55]
	v_mov_b32_e32 v54, v53
	v_mov_b32_e32 v5, v14
	s_waitcnt vmcnt(4)
	v_mul_f32_e32 v14, v10, v56
	v_mul_f32_e32 v15, v12, v58
	v_pk_fma_f32 v[2:3], v[2:3], v[54:55], v[4:5]
	v_fmac_f32_e32 v14, v11, v57
	v_fmac_f32_e32 v15, v13, v59
	v_add_f32_e32 v2, v2, v3
	v_add_f32_e32 v3, v14, v15
	s_nop 0
	v_add_f32_dpp v2, v2, v2 row_ror:8 row_mask:0xf bank_mask:0xf bound_ctrl:1
	v_add_f32_dpp v3, v3, v3 row_ror:8 row_mask:0xf bank_mask:0xf bound_ctrl:1
	s_nop 0
	v_add_f32_dpp v2, v2, v2 row_ror:4 row_mask:0xf bank_mask:0xf bound_ctrl:1
	v_add_f32_dpp v3, v3, v3 row_ror:4 row_mask:0xf bank_mask:0xf bound_ctrl:1
	s_nop 0
	v_add_f32_dpp v4, v2, v2 row_ror:2 row_mask:0xf bank_mask:0xf bound_ctrl:1
	v_add_f32_dpp v2, v3, v3 row_ror:2 row_mask:0xf bank_mask:0xf bound_ctrl:1
	s_nop 0
	v_add_f32_dpp v50, v4, v4 row_ror:1 row_mask:0xf bank_mask:0xf bound_ctrl:1
	v_mov_b32_dpp v22, v2 row_ror:1 row_mask:0xf bank_mask:0xf
	s_and_saveexec_b64 s[4:5], vcc
	s_cbranch_execz .LBB0_1226
	s_lshl_b64 s[38:39], s[20:21], 9
	v_lshl_add_u64 v[14:15], s[38:39], 2, v[42:43]
	s_waitcnt vmcnt(0)
	v_mul_f32_e32 v3, v50, v64
	v_mul_f32_e32 v23, v48, v65
	v_pk_add_f32 v[2:3], v[2:3], v[22:23]
	s_nop 0
	v_fmac_f32_e32 v2, 0x41800000, v3
	global_store_dword v[14:15], v2, off
; #define GAS __attribute__((address_space(1)))
; DI float dot4(const f32x4& x, const f32x4& y) { return fmaf(x.y, y.y, x.x * y.x) + fmaf(x.w, y.w, x.z * y.z); }
; DI void sscan_wave(const float* SC5, const float* RKV, const float* SCAL, float* Y, const float* init, float* fin, int chain, int rg, int lane) {
;     ...
; #pragma unroll
;     for (int t = 0; t < DS; ++t) {
;         const size_t m = (size_t)MP + (size_t)b * DS + t; const float* p5 = SC5 + m * RWD + hd * 64 + 4 * j;
;         const f32x4 a4 = *(const GAS f32x4*)p5, wr4 = *(const GAS f32x4*)(p5 + ASZ), w4 = *(const GAS f32x4*)(p5 + 2 * ASZ), b4 = *(const GAS f32x4*)(p5 + 3 * ASZ), k4 = *(const GAS f32x4*)(p5 + 4 * ASZ);
;         const float vv = ((const GAS float*)RKV)[m * 1536 + 1024 + hd * 64 + row]; const f32x2 sc = *(const GAS f32x2*)(SCAL + (m * 8 + hd) * 4);
;         const float sa = rowsum16(dot4(s, a4)), y1 = rowsum16(dot4(s, wr4));
;         s = s * w4 + b4 * sa + k4 * vv;
;         if (j == 0) ((GAS float*)Y)[m * RWD + hd * 64 + row] = y1 + 16.f * (sa * sc.x + vv * sc.y);
;     }
;     *(GAS f32x4*)(fin + (size_t)chain * 4096 + (size_t)row * 64 + 4 * j) = s;
.LBB0_1226:
	s_or_b64 exec, exec, s[4:5]
	s_add_u32 s20, s18, 0x8004
	s_addc_u32 s21, s19, 0
	s_lshl_b64 s[4:5], s[20:21], 11
	v_lshl_add_u64 v[14:15], v[44:45], 0, s[4:5]
	v_add_co_u32_e64 v2, s[4:5], s25, v14
	s_add_u32 s36, s36, 0x1800
	s_nop 0
	v_addc_co_u32_e64 v3, s[4:5], 0, v15, s[4:5]
	global_load_dwordx4 v[52:55], v[14:15], off
	global_load_dwordx4 v[56:59], v[2:3], off
	v_add_co_u32_e64 v2, s[4:5], s26, v14
	s_addc_u32 s37, s37, 0
	s_nop 0
	v_addc_co_u32_e64 v3, s[4:5], 0, v15, s[4:5]
	v_add_co_u32_e64 v16, s[4:5], s27, v14
	s_waitcnt vmcnt(4)
	v_pk_mul_f32 v[28:29], v[28:29], v[50:51] op_sel_hi:[1,0]
	v_addc_co_u32_e64 v17, s[4:5], 0, v15, s[4:5]
	v_add_co_u32_e64 v14, s[4:5], s28, v14
	global_load_dwordx4 v[2:5], v[2:3], off
	s_nop 0
	global_load_dwordx4 v[22:25], v[16:17], off
	v_addc_co_u32_e64 v15, s[4:5], 0, v15, s[4:5]
	s_add_u32 s4, s36, s12
	s_addc_u32 s5, s37, 0
	v_lshl_add_u64 v[16:17], s[4:5], 0, v[30:31]
	v_add_co_u32_e64 v46, s[4:5], s29, v16
	v_pk_mul_f32 v[50:51], v[26:27], v[50:51] op_sel_hi:[1,0]
	s_nop 0
	v_addc_co_u32_e64 v47, s[4:5], 0, v17, s[4:5]
	global_load_dwordx4 v[14:17], v[14:15], off
	s_nop 0
	global_load_dword v46, v[46:47], off
	s_lshl_b64 s[98:99], s[20:21], 7
	s_add_u32 s98, s15, s98
	s_addc_u32 s99, s35, s99
	global_load_dwordx2 v[64:65], v31, s[98:99]
	v_pk_fma_f32 v[8:9], v[12:13], v[8:9], v[28:29]
	v_pk_fma_f32 v[6:7], v[10:11], v[6:7], v[50:51]
	s_waitcnt vmcnt(6)
	v_pk_fma_f32 v[28:29], v[20:21], v[48:49], v[8:9] op_sel_hi:[1,0,1]
	v_pk_fma_f32 v[48:49], v[18:19], v[48:49], v[6:7] op_sel_hi:[1,0,1]
	v_mov_b32_e32 v7, v29
	v_mov_b32_e32 v6, v49
	v_mov_b32_e32 v26, v31
	s_waitcnt vmcnt(5)
	v_pk_mul_f32 v[8:9], v[48:49], v[52:53]
	v_pk_mul_f32 v[10:11], v[28:29], v[54:55]
	v_mov_b32_e32 v54, v53
	v_mov_b32_e32 v9, v10
	s_waitcnt vmcnt(4)
	v_mul_f32_e32 v10, v48, v56
	v_mul_f32_e32 v11, v28, v58
	v_pk_fma_f32 v[6:7], v[6:7], v[54:55], v[8:9]
	v_fmac_f32_e32 v10, v49, v57
	v_fmac_f32_e32 v11, v29, v59
	v_add_f32_e32 v6, v6, v7
	v_add_f32_e32 v7, v10, v11
	s_nop 0
	v_add_f32_dpp v6, v6, v6 row_ror:8 row_mask:0xf bank_mask:0xf bound_ctrl:1
	v_add_f32_dpp v7, v7, v7 row_ror:8 row_mask:0xf bank_mask:0xf bound_ctrl:1
	s_nop 0
	v_add_f32_dpp v6, v6, v6 row_ror:4 row_mask:0xf bank_mask:0xf bound_ctrl:1
	v_add_f32_dpp v7, v7, v7 row_ror:4 row_mask:0xf bank_mask:0xf bound_ctrl:1
	s_nop 0
	v_add_f32_dpp v8, v6, v6 row_ror:2 row_mask:0xf bank_mask:0xf bound_ctrl:1
	v_add_f32_dpp v6, v7, v7 row_ror:2 row_mask:0xf bank_mask:0xf bound_ctrl:1
	s_nop 0
	v_add_f32_dpp v50, v8, v8 row_ror:1 row_mask:0xf bank_mask:0xf bound_ctrl:1
	v_mov_b32_dpp v26, v6 row_ror:1 row_mask:0xf bank_mask:0xf
	s_and_saveexec_b64 s[4:5], vcc
	s_cbranch_execz .LBB0_1228
	s_lshl_b64 s[38:39], s[20:21], 9
	v_lshl_add_u64 v[10:11], s[38:39], 2, v[42:43]
	s_waitcnt vmcnt(0)
	v_mul_f32_e32 v7, v50, v64
	v_mul_f32_e32 v27, v46, v65
	v_pk_add_f32 v[6:7], v[6:7], v[26:27]
	s_nop 0
	v_fmac_f32_e32 v6, 0x41800000, v7
	global_store_dword v[10:11], v6, off
.LBB0_1228:
	s_or_b64 exec, exec, s[4:5]
	s_add_u32 s20, s18, 0x8005
	s_addc_u32 s21, s19, 0
	s_lshl_b64 s[4:5], s[20:21], 11
	v_lshl_add_u64 v[10:11], v[44:45], 0, s[4:5]
	v_add_co_u32_e64 v6, s[4:5], s25, v10
	s_add_u32 s36, s36, 0x1800
	s_nop 0
	v_addc_co_u32_e64 v7, s[4:5], 0, v11, s[4:5]
	global_load_dwordx4 v[52:55], v[10:11], off
	global_load_dwordx4 v[56:59], v[6:7], off
	v_add_co_u32_e64 v6, s[4:5], s26, v10
	s_addc_u32 s37, s37, 0
	s_nop 0
	v_addc_co_u32_e64 v7, s[4:5], 0, v11, s[4:5]
	v_add_co_u32_e64 v12, s[4:5], s27, v10
	s_waitcnt vmcnt(4)
	v_pk_mul_f32 v[24:25], v[24:25], v[50:51] op_sel_hi:[1,0]
	v_addc_co_u32_e64 v13, s[4:5], 0, v11, s[4:5]
	v_add_co_u32_e64 v10, s[4:5], s28, v10
	global_load_dwordx4 v[6:9], v[6:7], off
	s_nop 0
	global_load_dwordx4 v[18:21], v[12:13], off
	v_addc_co_u32_e64 v11, s[4:5], 0, v11, s[4:5]
	s_add_u32 s4, s36, s12
	s_addc_u32 s5, s37, 0
	v_lshl_add_u64 v[26:27], s[4:5], 0, v[30:31]
	v_add_co_u32_e64 v26, s[4:5], s29, v26
	global_load_dwordx4 v[10:13], v[10:11], off
	s_nop 0
	v_addc_co_u32_e64 v27, s[4:5], 0, v27, s[4:5]
	global_load_dword v26, v[26:27], off
	s_lshl_b64 s[98:99], s[20:21], 7
	s_add_u32 s98, s15, s98
	s_addc_u32 s99, s35, s99
	global_load_dwordx2 v[64:65], v31, s[98:99]
	v_pk_mul_f32 v[50:51], v[22:23], v[50:51] op_sel_hi:[1,0]
	v_pk_fma_f32 v[4:5], v[28:29], v[4:5], v[24:25]
	v_pk_fma_f32 v[2:3], v[48:49], v[2:3], v[50:51]
	s_waitcnt vmcnt(6)
	v_pk_fma_f32 v[48:49], v[16:17], v[46:47], v[4:5] op_sel_hi:[1,0,1]
	v_pk_fma_f32 v[46:47], v[14:15], v[46:47], v[2:3] op_sel_hi:[1,0,1]
	v_mov_b32_e32 v3, v49
	v_mov_b32_e32 v2, v47
	v_mov_b32_e32 v22, v31
	s_waitcnt vmcnt(5)
	v_pk_mul_f32 v[4:5], v[46:47], v[52:53]
	v_pk_mul_f32 v[14:15], v[48:49], v[54:55]
	v_mov_b32_e32 v54, v53
	v_mov_b32_e32 v5, v14
	s_waitcnt vmcnt(4)
	v_mul_f32_e32 v14, v46, v56
	v_mul_f32_e32 v15, v48, v58
	v_pk_fma_f32 v[2:3], v[2:3], v[54:55], v[4:5]
	v_fmac_f32_e32 v14, v47, v57
	v_fmac_f32_e32 v15, v49, v59
	v_add_f32_e32 v2, v2, v3
	v_add_f32_e32 v3, v14, v15
	s_nop 0
	v_add_f32_dpp v2, v2, v2 row_ror:8 row_mask:0xf bank_mask:0xf bound_ctrl:1
	v_add_f32_dpp v3, v3, v3 row_ror:8 row_mask:0xf bank_mask:0xf bound_ctrl:1
	s_nop 0
	v_add_f32_dpp v2, v2, v2 row_ror:4 row_mask:0xf bank_mask:0xf bound_ctrl:1
	v_add_f32_dpp v3, v3, v3 row_ror:4 row_mask:0xf bank_mask:0xf bound_ctrl:1
	s_nop 0
	v_add_f32_dpp v4, v2, v2 row_ror:2 row_mask:0xf bank_mask:0xf bound_ctrl:1
	v_add_f32_dpp v2, v3, v3 row_ror:2 row_mask:0xf bank_mask:0xf bound_ctrl:1
	s_nop 0
	v_add_f32_dpp v50, v4, v4 row_ror:1 row_mask:0xf bank_mask:0xf bound_ctrl:1
	v_mov_b32_dpp v22, v2 row_ror:1 row_mask:0xf bank_mask:0xf
	s_and_saveexec_b64 s[4:5], vcc
	s_cbranch_execz .LBB0_1230
	s_lshl_b64 s[38:39], s[20:21], 9
	v_lshl_add_u64 v[14:15], s[38:39], 2, v[42:43]
	s_waitcnt vmcnt(0)
	v_mul_f32_e32 v3, v50, v64
	v_mul_f32_e32 v23, v26, v65
	v_pk_add_f32 v[2:3], v[2:3], v[22:23]
	s_nop 0
	v_fmac_f32_e32 v2, 0x41800000, v3
	global_store_dword v[14:15], v2, off
; #define GAS __attribute__((address_space(1)))
; DI float dot4(const f32x4& x, const f32x4& y) { return fmaf(x.y, y.y, x.x * y.x) + fmaf(x.w, y.w, x.z * y.z); }
; DI void sscan_wave(const float* SC5, const float* RKV, const float* SCAL, float* Y, const float* init, float* fin, int chain, int rg, int lane) {
;     ...
; #pragma unroll
;     for (int t = 0; t < DS; ++t) {
;         const size_t m = (size_t)MP + (size_t)b * DS + t; const float* p5 = SC5 + m * RWD + hd * 64 + 4 * j;
;         const f32x4 a4 = *(const GAS f32x4*)p5, wr4 = *(const GAS f32x4*)(p5 + ASZ), w4 = *(const GAS f32x4*)(p5 + 2 * ASZ), b4 = *(const GAS f32x4*)(p5 + 3 * ASZ), k4 = *(const GAS f32x4*)(p5 + 4 * ASZ);
;         const float vv = ((const GAS float*)RKV)[m * 1536 + 1024 + hd * 64 + row]; const f32x2 sc = *(const GAS f32x2*)(SCAL + (m * 8 + hd) * 4);
;         const float sa = rowsum16(dot4(s, a4)), y1 = rowsum16(dot4(s, wr4));
;         s = s * w4 + b4 * sa + k4 * vv;
;         if (j == 0) ((GAS float*)Y)[m * RWD + hd * 64 + row] = y1 + 16.f * (sa * sc.x + vv * sc.y);
;     }
;     *(GAS f32x4*)(fin + (size_t)chain * 4096 + (size_t)row * 64 + 4 * j) = s;
.LBB0_1230:
	s_or_b64 exec, exec, s[4:5]
	s_add_u32 s20, s18, 0x8006
	s_addc_u32 s21, s19, 0
	s_lshl_b64 s[4:5], s[20:21], 11
	v_lshl_add_u64 v[22:23], v[44:45], 0, s[4:5]
	v_add_co_u32_e64 v2, s[4:5], s25, v22
	s_add_u32 s36, s36, 0x1800
	s_nop 0
	v_addc_co_u32_e64 v3, s[4:5], 0, v23, s[4:5]
	global_load_dwordx4 v[52:55], v[22:23], off
	global_load_dwordx4 v[56:59], v[2:3], off
	v_add_co_u32_e64 v2, s[4:5], s26, v22
	s_addc_u32 s37, s37, 0
	s_nop 0
	v_addc_co_u32_e64 v3, s[4:5], 0, v23, s[4:5]
	v_add_co_u32_e64 v14, s[4:5], s27, v22
	s_waitcnt vmcnt(4)
	v_pk_mul_f32 v[20:21], v[20:21], v[50:51] op_sel_hi:[1,0]
	v_addc_co_u32_e64 v15, s[4:5], 0, v23, s[4:5]
	v_add_co_u32_e64 v22, s[4:5], s28, v22
	global_load_dwordx4 v[2:5], v[2:3], off
	s_nop 0
	global_load_dwordx4 v[14:17], v[14:15], off
	v_addc_co_u32_e64 v23, s[4:5], 0, v23, s[4:5]
	s_add_u32 s4, s36, s12
	s_addc_u32 s5, s37, 0
	v_lshl_add_u64 v[28:29], s[4:5], 0, v[30:31]
	v_add_co_u32_e64 v28, s[4:5], s29, v28
	global_load_dwordx4 v[22:25], v[22:23], off
	s_nop 0
	v_addc_co_u32_e64 v29, s[4:5], 0, v29, s[4:5]
	global_load_dword v28, v[28:29], off
	s_lshl_b64 s[98:99], s[20:21], 7
	s_add_u32 s98, s15, s98
	s_addc_u32 s99, s35, s99
	global_load_dwordx2 v[64:65], v31, s[98:99]
	v_pk_mul_f32 v[50:51], v[18:19], v[50:51] op_sel_hi:[1,0]
	v_pk_fma_f32 v[8:9], v[48:49], v[8:9], v[20:21]
	v_pk_fma_f32 v[6:7], v[46:47], v[6:7], v[50:51]
	s_waitcnt vmcnt(6)
	v_pk_fma_f32 v[46:47], v[12:13], v[26:27], v[8:9] op_sel_hi:[1,0,1]
	v_pk_fma_f32 v[26:27], v[10:11], v[26:27], v[6:7] op_sel_hi:[1,0,1]
	v_mov_b32_e32 v7, v47
	v_mov_b32_e32 v6, v27
	v_mov_b32_e32 v18, v31
	s_waitcnt vmcnt(5)
	v_pk_mul_f32 v[8:9], v[26:27], v[52:53]
	v_pk_mul_f32 v[10:11], v[46:47], v[54:55]
	v_mov_b32_e32 v54, v53
	v_mov_b32_e32 v9, v10
	s_waitcnt vmcnt(4)
	v_mul_f32_e32 v10, v26, v56
	v_mul_f32_e32 v11, v46, v58
	v_pk_fma_f32 v[6:7], v[6:7], v[54:55], v[8:9]
	v_fmac_f32_e32 v10, v27, v57
	v_fmac_f32_e32 v11, v47, v59
	v_add_f32_e32 v6, v6, v7
	v_add_f32_e32 v7, v10, v11
	s_nop 0
	v_add_f32_dpp v6, v6, v6 row_ror:8 row_mask:0xf bank_mask:0xf bound_ctrl:1
	v_add_f32_dpp v7, v7, v7 row_ror:8 row_mask:0xf bank_mask:0xf bound_ctrl:1
	s_nop 0
	v_add_f32_dpp v6, v6, v6 row_ror:4 row_mask:0xf bank_mask:0xf bound_ctrl:1
	v_add_f32_dpp v7, v7, v7 row_ror:4 row_mask:0xf bank_mask:0xf bound_ctrl:1
	s_nop 0
	v_add_f32_dpp v8, v6, v6 row_ror:2 row_mask:0xf bank_mask:0xf bound_ctrl:1
	v_add_f32_dpp v6, v7, v7 row_ror:2 row_mask:0xf bank_mask:0xf bound_ctrl:1
	s_nop 0
	v_add_f32_dpp v48, v8, v8 row_ror:1 row_mask:0xf bank_mask:0xf bound_ctrl:1
	v_mov_b32_dpp v18, v6 row_ror:1 row_mask:0xf bank_mask:0xf
	s_and_saveexec_b64 s[4:5], vcc
	s_cbranch_execz .LBB0_1232
	s_lshl_b64 s[38:39], s[20:21], 9
	v_lshl_add_u64 v[10:11], s[38:39], 2, v[42:43]
	s_waitcnt vmcnt(0)
	v_mul_f32_e32 v7, v48, v64
	v_mul_f32_e32 v19, v28, v65
	v_pk_add_f32 v[6:7], v[6:7], v[18:19]
	s_nop 0
	v_fmac_f32_e32 v6, 0x41800000, v7
	global_store_dword v[10:11], v6, off
.LBB0_1232:
	s_or_b64 exec, exec, s[4:5]
	s_lshl_b64 s[20:21], s[16:17], 12
	s_add_u32 s18, s18, 0x8007
	s_addc_u32 s19, s19, 0
	s_lshl_b64 s[4:5], s[18:19], 11
	v_lshl_add_u64 v[10:11], v[44:45], 0, s[4:5]
	v_add_co_u32_e64 v6, s[4:5], s25, v10
	s_waitcnt vmcnt(2)
	v_pk_mul_f32 v[16:17], v[16:17], v[48:49] op_sel_hi:[1,0]
	v_addc_co_u32_e64 v7, s[4:5], 0, v11, s[4:5]
	global_load_dwordx4 v[50:53], v[10:11], off
	global_load_dwordx4 v[54:57], v[6:7], off
	v_add_co_u32_e64 v6, s[4:5], s26, v10
	v_pk_mul_f32 v[14:15], v[14:15], v[48:49] op_sel_hi:[1,0]
	s_nop 0
	v_addc_co_u32_e64 v7, s[4:5], 0, v11, s[4:5]
	v_add_co_u32_e64 v12, s[4:5], s27, v10
	v_pk_fma_f32 v[4:5], v[46:47], v[4:5], v[16:17]
	s_nop 0
	v_addc_co_u32_e64 v13, s[4:5], 0, v11, s[4:5]
	v_add_co_u32_e64 v10, s[4:5], s28, v10
	global_load_dwordx4 v[6:9], v[6:7], off
	s_nop 0
	global_load_dwordx4 v[18:21], v[12:13], off
	v_addc_co_u32_e64 v11, s[4:5], 0, v11, s[4:5]
	s_add_u32 s4, s36, s12
	s_addc_u32 s5, s37, 0
	v_lshl_add_u64 v[44:45], s[4:5], 0, v[30:31]
	v_add_co_u32_e64 v44, s[4:5], s30, v44
	global_load_dwordx4 v[10:13], v[10:11], off
	s_nop 0
	v_addc_co_u32_e64 v45, s[4:5], 0, v45, s[4:5]
	global_load_dword v44, v[44:45], off offset:2048
	s_lshl_b64 s[98:99], s[18:19], 7
	s_add_u32 s98, s15, s98
	s_addc_u32 s99, s35, s99
	global_load_dwordx2 v[64:65], v31, s[98:99]
	v_pk_fma_f32 v[14:15], v[26:27], v[2:3], v[14:15]
	s_waitcnt vmcnt(6)
	v_pk_fma_f32 v[2:3], v[24:25], v[28:29], v[4:5] op_sel_hi:[1,0,1]
	v_pk_fma_f32 v[4:5], v[22:23], v[28:29], v[14:15] op_sel_hi:[1,0,1]
	v_mov_b32_e32 v22, v31
	s_waitcnt vmcnt(5)
	v_mul_f32_e32 v14, v4, v50
	v_mul_f32_e32 v15, v2, v52
	s_waitcnt vmcnt(4)
	v_mul_f32_e32 v16, v4, v54
	v_mul_f32_e32 v17, v2, v56
	v_fmac_f32_e32 v14, v5, v51
	v_fmac_f32_e32 v15, v3, v53
	v_fmac_f32_e32 v16, v5, v55
	v_fmac_f32_e32 v17, v3, v57
	v_add_f32_e32 v14, v14, v15
	v_add_f32_e32 v15, v16, v17
	s_nop 0
	v_add_f32_dpp v14, v14, v14 row_ror:8 row_mask:0xf bank_mask:0xf bound_ctrl:1
	v_add_f32_dpp v15, v15, v15 row_ror:8 row_mask:0xf bank_mask:0xf bound_ctrl:1
	s_nop 0
	v_add_f32_dpp v14, v14, v14 row_ror:4 row_mask:0xf bank_mask:0xf bound_ctrl:1
	v_add_f32_dpp v15, v15, v15 row_ror:4 row_mask:0xf bank_mask:0xf bound_ctrl:1
	s_nop 0
	v_add_f32_dpp v14, v14, v14 row_ror:2 row_mask:0xf bank_mask:0xf bound_ctrl:1
	v_add_f32_dpp v16, v15, v15 row_ror:2 row_mask:0xf bank_mask:0xf bound_ctrl:1
	s_nop 0
	v_add_f32_dpp v14, v14, v14 row_ror:1 row_mask:0xf bank_mask:0xf bound_ctrl:1
	v_mov_b32_dpp v22, v16 row_ror:1 row_mask:0xf bank_mask:0xf
	s_and_saveexec_b64 s[4:5], vcc
	s_cbranch_execz .LBB0_1234
	s_lshl_b64 s[36:37], s[18:19], 9
	v_lshl_add_u64 v[26:27], s[36:37], 2, v[42:43]
	s_waitcnt vmcnt(0)
	v_mul_f32_e32 v17, v14, v64
	v_mul_f32_e32 v23, v44, v65
	v_pk_add_f32 v[16:17], v[16:17], v[22:23]
	s_nop 0
	v_fmac_f32_e32 v16, 0x41800000, v17
	global_store_dword v[26:27], v16, off
; #define GAS __attribute__((address_space(1)))
; DI float dot4(const f32x4& x, const f32x4& y) { return fmaf(x.y, y.y, x.x * y.x) + fmaf(x.w, y.w, x.z * y.z); }
; DI void sscan_wave(const float* SC5, const float* RKV, const float* SCAL, float* Y, const float* init, float* fin, int chain, int rg, int lane) {
;     ...
;     f32x4 s = *(const GAS f32x4*)(init + (size_t)chain * 4096 + (size_t)row * 64 + 4 * j);
; #pragma unroll
;     for (int t = 0; t < DS; ++t) {
;         const size_t m = (size_t)MP + (size_t)b * DS + t; const float* p5 = SC5 + m * RWD + hd * 64 + 4 * j;
;         const f32x4 a4 = *(const GAS f32x4*)p5, wr4 = *(const GAS f32x4*)(p5 + ASZ), w4 = *(const GAS f32x4*)(p5 + 2 * ASZ), b4 = *(const GAS f32x4*)(p5 + 3 * ASZ), k4 = *(const GAS f32x4*)(p5 + 4 * ASZ);
;         const float vv = ((const GAS float*)RKV)[m * 1536 + 1024 + hd * 64 + row]; const f32x2 sc = *(const GAS f32x2*)(SCAL + (m * 8 + hd) * 4);
;         const float sa = rowsum16(dot4(s, a4)), y1 = rowsum16(dot4(s, wr4));
;         s = s * w4 + b4 * sa + k4 * vv;
;         if (j == 0) ((GAS float*)Y)[m * RWD + hd * 64 + row] = y1 + 16.f * (sa * sc.x + vv * sc.y);
;     }
;     *(GAS f32x4*)(fin + (size_t)chain * 4096 + (size_t)row * 64 + 4 * j) = s;
.LBB0_1234:
	s_or_b64 exec, exec, s[4:5]
	s_waitcnt vmcnt(2)
	v_pk_mul_f32 v[16:17], v[20:21], v[14:15] op_sel_hi:[1,0]
	v_pk_mul_f32 v[14:15], v[18:19], v[14:15] op_sel_hi:[1,0]
	s_ashr_i32 s15, s14, 31
	v_pk_fma_f32 v[8:9], v[2:3], v[8:9], v[16:17]
	v_pk_fma_f32 v[2:3], v[4:5], v[6:7], v[14:15]
	s_ashr_i32 s4, s14, 3
	s_and_b32 s36, s14, 7
	s_add_i32 s5, s22, s34
	s_lshl_b64 s[18:19], s[14:15], 14
	s_waitcnt vmcnt(0)
	v_pk_fma_f32 v[2:3], v[10:11], v[44:45], v[2:3] op_sel_hi:[1,0,1]
	v_pk_fma_f32 v[4:5], v[12:13], v[44:45], v[8:9] op_sel_hi:[1,0,1]
	v_lshl_add_u64 v[6:7], s[20:21], 2, v[38:39]
	v_and_or_b32 v53, s5, 60, v155
	s_add_u32 s18, s6, s18
	global_store_dwordx4 v[6:7], v[2:5], off
	s_addc_u32 s19, s7, s19
	s_ashr_i32 s5, s4, 31
	v_lshlrev_b32_e32 v2, 8, v53
	v_mov_b32_e32 v3, v31
	v_lshl_add_u64 v[2:3], s[18:19], 0, v[2:3]
	s_lshl_b64 s[18:19], s[4:5], 3
	s_add_u32 s20, s18, 0x8000
	s_addc_u32 s21, s19, 0
	s_lshl_b32 s12, s36, 8
	s_add_u32 s40, s8, s12
	s_addc_u32 s41, s9, 0
	s_lshl_b32 s4, s36, 4
	s_add_u32 s17, s74, s4
	v_lshl_add_u64 v[46:47], v[32:33], 0, s[12:13]
	s_addc_u32 s35, s75, 0
	s_lshl_b64 s[4:5], s[20:21], 11
	v_lshl_add_u64 v[18:19], v[46:47], 0, s[4:5]
	v_add_co_u32_e64 v10, s[4:5], s25, v18
	v_mov_b32_e32 v41, v31
	s_nop 0
	v_addc_co_u32_e64 v11, s[4:5], 0, v19, s[4:5]
	v_add_co_u32_e64 v14, s[4:5], s26, v18
	v_lshl_add_u64 v[2:3], v[2:3], 0, v[40:41]
	s_nop 0
	v_addc_co_u32_e64 v15, s[4:5], 0, v19, s[4:5]
	v_add_co_u32_e64 v20, s[4:5], s27, v18
	global_load_dwordx4 v[2:5], v[2:3], off
	s_nop 0
	v_addc_co_u32_e64 v21, s[4:5], 0, v19, s[4:5]
	global_load_dwordx4 v[6:9], v[18:19], off
	s_nop 0
	global_load_dwordx4 v[10:13], v[10:11], off
	v_add_co_u32_e64 v18, s[4:5], s28, v18
	v_lshlrev_b32_e32 v44, 2, v53
	s_nop 0
	v_addc_co_u32_e64 v19, s[4:5], 0, v19, s[4:5]
	s_mul_i32 s4, s21, 0x1800
	s_mul_hi_u32 s5, s20, 0x1800
	s_add_i32 s5, s5, s4
	s_mul_i32 s4, s20, 0x1800
	s_add_u32 s37, s0, s4
	s_addc_u32 s38, s1, s5
	s_add_u32 s4, s37, s12
	v_mov_b32_e32 v45, v31
	s_addc_u32 s5, s38, 0
	global_load_dwordx4 v[14:17], v[14:15], off
	s_nop 0
	global_load_dwordx4 v[26:29], v[20:21], off
	v_lshl_add_u64 v[20:21], s[4:5], 0, v[44:45]
	v_add_co_u32_e64 v20, s[4:5], s29, v20
	v_lshl_add_u64 v[42:43], s[40:41], 0, v[44:45]
	s_nop 0
	v_addc_co_u32_e64 v21, s[4:5], 0, v21, s[4:5]
	global_load_dwordx4 v[22:25], v[18:19], off
	global_load_dword v50, v[20:21], off
	s_lshl_b64 s[98:99], s[20:21], 7
	s_add_u32 s98, s17, s98
	s_addc_u32 s99, s35, s99
	global_load_dwordx2 v[64:65], v31, s[98:99]
	s_waitcnt vmcnt(6)
	v_mov_b32_e32 v18, v3
	v_mov_b32_e32 v19, v5
	s_waitcnt vmcnt(5)
	v_mul_f32_e32 v20, v2, v6
	v_mul_f32_e32 v21, v4, v8
	v_mov_b32_e32 v8, v7
	v_pk_fma_f32 v[6:7], v[18:19], v[8:9], v[20:21]
	s_waitcnt vmcnt(4)
	v_mul_f32_e32 v8, v2, v10
	v_mul_f32_e32 v9, v4, v12
	v_add_f32_e32 v6, v6, v7
	v_fmac_f32_e32 v8, v3, v11
	v_fmac_f32_e32 v9, v5, v13
	v_add_f32_dpp v6, v6, v6 row_ror:8 row_mask:0xf bank_mask:0xf bound_ctrl:1
	v_add_f32_e32 v7, v8, v9
	v_mov_b32_e32 v8, v31
	v_add_f32_dpp v6, v6, v6 row_ror:4 row_mask:0xf bank_mask:0xf bound_ctrl:1
	v_add_f32_dpp v7, v7, v7 row_ror:8 row_mask:0xf bank_mask:0xf bound_ctrl:1
	s_nop 0
	v_add_f32_dpp v6, v6, v6 row_ror:2 row_mask:0xf bank_mask:0xf bound_ctrl:1
	v_add_f32_dpp v7, v7, v7 row_ror:4 row_mask:0xf bank_mask:0xf bound_ctrl:1
	s_nop 0
	v_add_f32_dpp v52, v6, v6 row_ror:1 row_mask:0xf bank_mask:0xf bound_ctrl:1
	v_add_f32_dpp v6, v7, v7 row_ror:2 row_mask:0xf bank_mask:0xf bound_ctrl:1
	s_nop 1
	v_mov_b32_dpp v8, v6 row_ror:1 row_mask:0xf bank_mask:0xf
	s_and_saveexec_b64 s[4:5], vcc
	s_cbranch_execz .LBB0_1236
	s_lshl_b64 s[40:41], s[20:21], 9
	v_lshl_add_u64 v[12:13], s[40:41], 2, v[42:43]
	s_waitcnt vmcnt(0)
	v_mul_f32_e32 v7, v52, v64
	v_mul_f32_e32 v9, v50, v65
	v_pk_add_f32 v[6:7], v[6:7], v[8:9]
	s_nop 0
	v_fmac_f32_e32 v6, 0x41800000, v7
	global_store_dword v[12:13], v6, off
.LBB0_1236:
	s_or_b64 exec, exec, s[4:5]
	s_lshl_b32 s12, s36, 6
	s_add_u32 s20, s18, 0x8001
	s_addc_u32 s21, s19, 0
	s_lshl_b64 s[4:5], s[20:21], 11
	v_lshl_add_u64 v[10:11], v[46:47], 0, s[4:5]
	v_add_co_u32_e64 v6, s[4:5], s25, v10
	s_add_u32 s36, s37, 0x1800
	s_nop 0
	v_addc_co_u32_e64 v7, s[4:5], 0, v11, s[4:5]
	global_load_dwordx4 v[54:57], v[10:11], off
	global_load_dwordx4 v[58:61], v[6:7], off
	v_add_co_u32_e64 v6, s[4:5], s26, v10
	s_addc_u32 s37, s38, 0
	s_nop 0
	v_addc_co_u32_e64 v7, s[4:5], 0, v11, s[4:5]
	v_add_co_u32_e64 v12, s[4:5], s27, v10
	s_lshl_b32 s12, s12, 2
	s_nop 0
	v_addc_co_u32_e64 v13, s[4:5], 0, v11, s[4:5]
	v_add_co_u32_e64 v10, s[4:5], s28, v10
	global_load_dwordx4 v[6:9], v[6:7], off
	s_nop 0
	global_load_dwordx4 v[18:21], v[12:13], off
	v_addc_co_u32_e64 v11, s[4:5], 0, v11, s[4:5]
	s_add_u32 s4, s36, s12
	s_addc_u32 s5, s37, 0
	v_lshl_add_u64 v[12:13], s[4:5], 0, v[44:45]
	v_add_co_u32_e64 v48, s[4:5], s29, v12
	s_waitcnt vmcnt(6)
	v_pk_mul_f32 v[62:63], v[28:29], v[52:53] op_sel_hi:[1,0]
	v_addc_co_u32_e64 v49, s[4:5], 0, v13, s[4:5]
	global_load_dwordx4 v[10:13], v[10:11], off
	s_nop 0
	global_load_dword v48, v[48:49], off
	s_lshl_b64 s[98:99], s[20:21], 7
	s_add_u32 s98, s17, s98
	s_addc_u32 s99, s35, s99
	global_load_dwordx2 v[64:65], v31, s[98:99]
	v_pk_mul_f32 v[26:27], v[26:27], v[52:53] op_sel_hi:[1,0]
	v_pk_fma_f32 v[4:5], v[4:5], v[16:17], v[62:63]
	v_pk_fma_f32 v[2:3], v[2:3], v[14:15], v[26:27]
	s_waitcnt vmcnt(6)
	v_pk_fma_f32 v[26:27], v[24:25], v[50:51], v[4:5] op_sel_hi:[1,0,1]
	v_pk_fma_f32 v[50:51], v[22:23], v[50:51], v[2:3] op_sel_hi:[1,0,1]
	v_mov_b32_e32 v3, v27
	v_mov_b32_e32 v2, v51
	v_mov_b32_e32 v28, v31
	s_waitcnt vmcnt(5)
	v_pk_mul_f32 v[4:5], v[50:51], v[54:55]
	v_pk_mul_f32 v[14:15], v[26:27], v[56:57]
	v_mov_b32_e32 v56, v55
	v_mov_b32_e32 v5, v14
	s_waitcnt vmcnt(4)
	v_mul_f32_e32 v14, v50, v58
	v_mul_f32_e32 v15, v26, v60
	v_pk_fma_f32 v[2:3], v[2:3], v[56:57], v[4:5]
	v_fmac_f32_e32 v14, v51, v59
	v_fmac_f32_e32 v15, v27, v61
	v_add_f32_e32 v2, v2, v3
	v_add_f32_e32 v3, v14, v15
	s_nop 0
	v_add_f32_dpp v2, v2, v2 row_ror:8 row_mask:0xf bank_mask:0xf bound_ctrl:1
	v_add_f32_dpp v3, v3, v3 row_ror:8 row_mask:0xf bank_mask:0xf bound_ctrl:1
	s_nop 0
	v_add_f32_dpp v2, v2, v2 row_ror:4 row_mask:0xf bank_mask:0xf bound_ctrl:1
	v_add_f32_dpp v3, v3, v3 row_ror:4 row_mask:0xf bank_mask:0xf bound_ctrl:1
	s_nop 0
	v_add_f32_dpp v4, v2, v2 row_ror:2 row_mask:0xf bank_mask:0xf bound_ctrl:1
	v_add_f32_dpp v2, v3, v3 row_ror:2 row_mask:0xf bank_mask:0xf bound_ctrl:1
	s_nop 0
	v_add_f32_dpp v52, v4, v4 row_ror:1 row_mask:0xf bank_mask:0xf bound_ctrl:1
	v_mov_b32_dpp v28, v2 row_ror:1 row_mask:0xf bank_mask:0xf
	s_and_saveexec_b64 s[4:5], vcc
	s_cbranch_execz .LBB0_1238
	s_lshl_b64 s[38:39], s[20:21], 9
	v_lshl_add_u64 v[14:15], s[38:39], 2, v[42:43]
	s_waitcnt vmcnt(0)
	v_mul_f32_e32 v3, v52, v64
	v_mul_f32_e32 v29, v48, v65
	v_pk_add_f32 v[2:3], v[2:3], v[28:29]
	s_nop 0
	v_fmac_f32_e32 v2, 0x41800000, v3
	global_store_dword v[14:15], v2, off
; #define GAS __attribute__((address_space(1)))
; DI float dot4(const f32x4& x, const f32x4& y) { return fmaf(x.y, y.y, x.x * y.x) + fmaf(x.w, y.w, x.z * y.z); }
; DI void sscan_wave(const float* SC5, const float* RKV, const float* SCAL, float* Y, const float* init, float* fin, int chain, int rg, int lane) {
;     ...
; #pragma unroll
;     for (int t = 0; t < DS; ++t) {
;         const size_t m = (size_t)MP + (size_t)b * DS + t; const float* p5 = SC5 + m * RWD + hd * 64 + 4 * j;
;         const f32x4 a4 = *(const GAS f32x4*)p5, wr4 = *(const GAS f32x4*)(p5 + ASZ), w4 = *(const GAS f32x4*)(p5 + 2 * ASZ), b4 = *(const GAS f32x4*)(p5 + 3 * ASZ), k4 = *(const GAS f32x4*)(p5 + 4 * ASZ);
;         const float vv = ((const GAS float*)RKV)[m * 1536 + 1024 + hd * 64 + row]; const f32x2 sc = *(const GAS f32x2*)(SCAL + (m * 8 + hd) * 4);
;         const float sa = rowsum16(dot4(s, a4)), y1 = rowsum16(dot4(s, wr4));
;         s = s * w4 + b4 * sa + k4 * vv;
;         if (j == 0) ((GAS float*)Y)[m * RWD + hd * 64 + row] = y1 + 16.f * (sa * sc.x + vv * sc.y);
;     }
;     *(GAS f32x4*)(fin + (size_t)chain * 4096 + (size_t)row * 64 + 4 * j) = s;
.LBB0_1238:
	s_or_b64 exec, exec, s[4:5]
	s_add_u32 s20, s18, 0x8002
	s_addc_u32 s21, s19, 0
	s_lshl_b64 s[4:5], s[20:21], 11
	v_lshl_add_u64 v[14:15], v[46:47], 0, s[4:5]
	v_add_co_u32_e64 v2, s[4:5], s25, v14
	s_add_u32 s36, s36, 0x1800
	s_nop 0
	v_addc_co_u32_e64 v3, s[4:5], 0, v15, s[4:5]
	global_load_dwordx4 v[54:57], v[14:15], off
	global_load_dwordx4 v[58:61], v[2:3], off
	v_add_co_u32_e64 v2, s[4:5], s26, v14
	s_addc_u32 s37, s37, 0
	s_nop 0
	v_addc_co_u32_e64 v3, s[4:5], 0, v15, s[4:5]
	v_add_co_u32_e64 v16, s[4:5], s27, v14
	v_mov_b32_e32 v45, v31
	s_nop 0
	v_addc_co_u32_e64 v17, s[4:5], 0, v15, s[4:5]
	v_add_co_u32_e64 v14, s[4:5], s28, v14
	global_load_dwordx4 v[2:5], v[2:3], off
	s_nop 0
	global_load_dwordx4 v[22:25], v[16:17], off
	v_addc_co_u32_e64 v15, s[4:5], 0, v15, s[4:5]
	s_add_u32 s4, s36, s12
	s_addc_u32 s5, s37, 0
	v_lshl_add_u64 v[16:17], s[4:5], 0, v[44:45]
	v_add_co_u32_e64 v28, s[4:5], s29, v16
	s_waitcnt vmcnt(6)
	v_pk_mul_f32 v[20:21], v[20:21], v[52:53] op_sel_hi:[1,0]
	v_addc_co_u32_e64 v29, s[4:5], 0, v17, s[4:5]
	global_load_dwordx4 v[14:17], v[14:15], off
	s_nop 0
	global_load_dword v28, v[28:29], off
	s_lshl_b64 s[98:99], s[20:21], 7
	s_add_u32 s98, s17, s98
	s_addc_u32 s99, s35, s99
	global_load_dwordx2 v[64:65], v31, s[98:99]
	v_pk_mul_f32 v[62:63], v[18:19], v[52:53] op_sel_hi:[1,0]
	v_pk_fma_f32 v[8:9], v[26:27], v[8:9], v[20:21]
	v_pk_fma_f32 v[6:7], v[50:51], v[6:7], v[62:63]
	s_waitcnt vmcnt(6)
	v_pk_fma_f32 v[50:51], v[12:13], v[48:49], v[8:9] op_sel_hi:[1,0,1]
	v_pk_fma_f32 v[48:49], v[10:11], v[48:49], v[6:7] op_sel_hi:[1,0,1]
	v_mov_b32_e32 v7, v51
	v_mov_b32_e32 v6, v49
	v_mov_b32_e32 v18, v31
	s_waitcnt vmcnt(5)
	v_pk_mul_f32 v[8:9], v[48:49], v[54:55]
	v_pk_mul_f32 v[10:11], v[50:51], v[56:57]
	v_mov_b32_e32 v56, v55
	v_mov_b32_e32 v9, v10
	s_waitcnt vmcnt(4)
	v_mul_f32_e32 v10, v48, v58
	v_mul_f32_e32 v11, v50, v60
	v_pk_fma_f32 v[6:7], v[6:7], v[56:57], v[8:9]
	v_fmac_f32_e32 v10, v49, v59
	v_fmac_f32_e32 v11, v51, v61
	v_add_f32_e32 v6, v6, v7
	v_add_f32_e32 v7, v10, v11
	s_nop 0
	v_add_f32_dpp v6, v6, v6 row_ror:8 row_mask:0xf bank_mask:0xf bound_ctrl:1
	v_add_f32_dpp v7, v7, v7 row_ror:8 row_mask:0xf bank_mask:0xf bound_ctrl:1
	s_nop 0
	v_add_f32_dpp v6, v6, v6 row_ror:4 row_mask:0xf bank_mask:0xf bound_ctrl:1
	v_add_f32_dpp v7, v7, v7 row_ror:4 row_mask:0xf bank_mask:0xf bound_ctrl:1
	s_nop 0
	v_add_f32_dpp v8, v6, v6 row_ror:2 row_mask:0xf bank_mask:0xf bound_ctrl:1
	v_add_f32_dpp v6, v7, v7 row_ror:2 row_mask:0xf bank_mask:0xf bound_ctrl:1
	s_nop 0
	v_add_f32_dpp v52, v8, v8 row_ror:1 row_mask:0xf bank_mask:0xf bound_ctrl:1
	v_mov_b32_dpp v18, v6 row_ror:1 row_mask:0xf bank_mask:0xf
	s_and_saveexec_b64 s[4:5], vcc
	s_cbranch_execz .LBB0_1240
	s_lshl_b64 s[38:39], s[20:21], 9
	v_lshl_add_u64 v[10:11], s[38:39], 2, v[42:43]
	s_waitcnt vmcnt(0)
	v_mul_f32_e32 v7, v52, v64
	v_mul_f32_e32 v19, v28, v65
	v_pk_add_f32 v[6:7], v[6:7], v[18:19]
	s_nop 0
	v_fmac_f32_e32 v6, 0x41800000, v7
	global_store_dword v[10:11], v6, off
.LBB0_1240:
	s_or_b64 exec, exec, s[4:5]
	s_add_u32 s20, s18, 0x8003
	s_addc_u32 s21, s19, 0
	s_lshl_b64 s[4:5], s[20:21], 11
	v_lshl_add_u64 v[10:11], v[46:47], 0, s[4:5]
	v_add_co_u32_e64 v6, s[4:5], s25, v10
	s_add_u32 s36, s36, 0x1800
	s_nop 0
	v_addc_co_u32_e64 v7, s[4:5], 0, v11, s[4:5]
	global_load_dwordx4 v[54:57], v[10:11], off
	global_load_dwordx4 v[58:61], v[6:7], off
	v_add_co_u32_e64 v6, s[4:5], s26, v10
	s_addc_u32 s37, s37, 0
	s_nop 0
	v_addc_co_u32_e64 v7, s[4:5], 0, v11, s[4:5]
	v_add_co_u32_e64 v12, s[4:5], s27, v10
	s_waitcnt vmcnt(4)
	v_pk_mul_f32 v[24:25], v[24:25], v[52:53] op_sel_hi:[1,0]
	v_addc_co_u32_e64 v13, s[4:5], 0, v11, s[4:5]
	v_add_co_u32_e64 v10, s[4:5], s28, v10
	global_load_dwordx4 v[6:9], v[6:7], off
	s_nop 0
	global_load_dwordx4 v[18:21], v[12:13], off
	v_addc_co_u32_e64 v11, s[4:5], 0, v11, s[4:5]
	s_add_u32 s4, s36, s12
	s_addc_u32 s5, s37, 0
	v_lshl_add_u64 v[12:13], s[4:5], 0, v[44:45]
	v_add_co_u32_e64 v26, s[4:5], s29, v12
	v_pk_mul_f32 v[62:63], v[22:23], v[52:53] op_sel_hi:[1,0]
	s_nop 0
	v_addc_co_u32_e64 v27, s[4:5], 0, v13, s[4:5]
	global_load_dwordx4 v[10:13], v[10:11], off
	s_nop 0
	global_load_dword v26, v[26:27], off
	s_lshl_b64 s[98:99], s[20:21], 7
	s_add_u32 s98, s17, s98
	s_addc_u32 s99, s35, s99
	global_load_dwordx2 v[64:65], v31, s[98:99]
	v_pk_fma_f32 v[4:5], v[50:51], v[4:5], v[24:25]
	v_pk_fma_f32 v[2:3], v[48:49], v[2:3], v[62:63]
	s_waitcnt vmcnt(6)
	v_pk_fma_f32 v[48:49], v[16:17], v[28:29], v[4:5] op_sel_hi:[1,0,1]
	v_pk_fma_f32 v[50:51], v[14:15], v[28:29], v[2:3] op_sel_hi:[1,0,1]
	v_mov_b32_e32 v3, v49
	v_mov_b32_e32 v2, v51
	v_mov_b32_e32 v22, v31
	s_waitcnt vmcnt(5)
	v_pk_mul_f32 v[4:5], v[50:51], v[54:55]
	v_pk_mul_f32 v[14:15], v[48:49], v[56:57]
	v_mov_b32_e32 v56, v55
	v_mov_b32_e32 v5, v14
	s_waitcnt vmcnt(4)
	v_mul_f32_e32 v14, v50, v58
	v_mul_f32_e32 v15, v48, v60
	v_pk_fma_f32 v[2:3], v[2:3], v[56:57], v[4:5]
	v_fmac_f32_e32 v14, v51, v59
	v_fmac_f32_e32 v15, v49, v61
	v_add_f32_e32 v2, v2, v3
	v_add_f32_e32 v3, v14, v15
	s_nop 0
	v_add_f32_dpp v2, v2, v2 row_ror:8 row_mask:0xf bank_mask:0xf bound_ctrl:1
	v_add_f32_dpp v3, v3, v3 row_ror:8 row_mask:0xf bank_mask:0xf bound_ctrl:1
	s_nop 0
	v_add_f32_dpp v2, v2, v2 row_ror:4 row_mask:0xf bank_mask:0xf bound_ctrl:1
	v_add_f32_dpp v3, v3, v3 row_ror:4 row_mask:0xf bank_mask:0xf bound_ctrl:1
	s_nop 0
	v_add_f32_dpp v4, v2, v2 row_ror:2 row_mask:0xf bank_mask:0xf bound_ctrl:1
	v_add_f32_dpp v2, v3, v3 row_ror:2 row_mask:0xf bank_mask:0xf bound_ctrl:1
	s_nop 0
	v_add_f32_dpp v52, v4, v4 row_ror:1 row_mask:0xf bank_mask:0xf bound_ctrl:1
	v_mov_b32_dpp v22, v2 row_ror:1 row_mask:0xf bank_mask:0xf
	s_and_saveexec_b64 s[4:5], vcc
	s_cbranch_execz .LBB0_1242
	s_lshl_b64 s[38:39], s[20:21], 9
	v_lshl_add_u64 v[14:15], s[38:39], 2, v[42:43]
	s_waitcnt vmcnt(0)
	v_mul_f32_e32 v3, v52, v64
	v_mul_f32_e32 v23, v26, v65
	v_pk_add_f32 v[2:3], v[2:3], v[22:23]
	s_nop 0
	v_fmac_f32_e32 v2, 0x41800000, v3
	global_store_dword v[14:15], v2, off
; #define GAS __attribute__((address_space(1)))
; DI float dot4(const f32x4& x, const f32x4& y) { return fmaf(x.y, y.y, x.x * y.x) + fmaf(x.w, y.w, x.z * y.z); }
; DI void sscan_wave(const float* SC5, const float* RKV, const float* SCAL, float* Y, const float* init, float* fin, int chain, int rg, int lane) {
;     ...
; #pragma unroll
;     for (int t = 0; t < DS; ++t) {
;         const size_t m = (size_t)MP + (size_t)b * DS + t; const float* p5 = SC5 + m * RWD + hd * 64 + 4 * j;
;         const f32x4 a4 = *(const GAS f32x4*)p5, wr4 = *(const GAS f32x4*)(p5 + ASZ), w4 = *(const GAS f32x4*)(p5 + 2 * ASZ), b4 = *(const GAS f32x4*)(p5 + 3 * ASZ), k4 = *(const GAS f32x4*)(p5 + 4 * ASZ);
;         const float vv = ((const GAS float*)RKV)[m * 1536 + 1024 + hd * 64 + row]; const f32x2 sc = *(const GAS f32x2*)(SCAL + (m * 8 + hd) * 4);
;         const float sa = rowsum16(dot4(s, a4)), y1 = rowsum16(dot4(s, wr4));
;         s = s * w4 + b4 * sa + k4 * vv;
;         if (j == 0) ((GAS float*)Y)[m * RWD + hd * 64 + row] = y1 + 16.f * (sa * sc.x + vv * sc.y);
;     }
;     *(GAS f32x4*)(fin + (size_t)chain * 4096 + (size_t)row * 64 + 4 * j) = s;
.LBB0_1242:
	s_or_b64 exec, exec, s[4:5]
	s_add_u32 s20, s18, 0x8004
	s_addc_u32 s21, s19, 0
	s_lshl_b64 s[4:5], s[20:21], 11
	v_lshl_add_u64 v[14:15], v[46:47], 0, s[4:5]
	v_add_co_u32_e64 v2, s[4:5], s25, v14
	s_add_u32 s36, s36, 0x1800
	s_nop 0
	v_addc_co_u32_e64 v3, s[4:5], 0, v15, s[4:5]
	global_load_dwordx4 v[54:57], v[14:15], off
	global_load_dwordx4 v[58:61], v[2:3], off
	v_add_co_u32_e64 v2, s[4:5], s26, v14
	s_addc_u32 s37, s37, 0
	s_nop 0
	v_addc_co_u32_e64 v3, s[4:5], 0, v15, s[4:5]
	v_add_co_u32_e64 v16, s[4:5], s27, v14
	v_mov_b32_e32 v45, v31
	s_nop 0
	v_addc_co_u32_e64 v17, s[4:5], 0, v15, s[4:5]
	v_add_co_u32_e64 v14, s[4:5], s28, v14
	global_load_dwordx4 v[2:5], v[2:3], off
	s_nop 0
	global_load_dwordx4 v[22:25], v[16:17], off
	v_addc_co_u32_e64 v15, s[4:5], 0, v15, s[4:5]
	s_add_u32 s4, s36, s12
	s_addc_u32 s5, s37, 0
	v_lshl_add_u64 v[16:17], s[4:5], 0, v[44:45]
	v_add_co_u32_e64 v28, s[4:5], s29, v16
	s_waitcnt vmcnt(6)
	v_pk_mul_f32 v[20:21], v[20:21], v[52:53] op_sel_hi:[1,0]
	v_addc_co_u32_e64 v29, s[4:5], 0, v17, s[4:5]
	global_load_dwordx4 v[14:17], v[14:15], off
	s_nop 0
	global_load_dword v28, v[28:29], off
	s_lshl_b64 s[98:99], s[20:21], 7
	s_add_u32 s98, s17, s98
	s_addc_u32 s99, s35, s99
	global_load_dwordx2 v[64:65], v31, s[98:99]
	v_pk_mul_f32 v[62:63], v[18:19], v[52:53] op_sel_hi:[1,0]
	v_pk_fma_f32 v[8:9], v[48:49], v[8:9], v[20:21]
	v_pk_fma_f32 v[6:7], v[50:51], v[6:7], v[62:63]
	s_waitcnt vmcnt(6)
	v_pk_fma_f32 v[48:49], v[12:13], v[26:27], v[8:9] op_sel_hi:[1,0,1]
	v_pk_fma_f32 v[50:51], v[10:11], v[26:27], v[6:7] op_sel_hi:[1,0,1]
	v_mov_b32_e32 v7, v49
	v_mov_b32_e32 v6, v51
	v_mov_b32_e32 v18, v31
	s_waitcnt vmcnt(5)
	v_pk_mul_f32 v[8:9], v[50:51], v[54:55]
	v_pk_mul_f32 v[10:11], v[48:49], v[56:57]
	v_mov_b32_e32 v56, v55
	v_mov_b32_e32 v9, v10
	s_waitcnt vmcnt(4)
	v_mul_f32_e32 v10, v50, v58
	v_mul_f32_e32 v11, v48, v60
	v_pk_fma_f32 v[6:7], v[6:7], v[56:57], v[8:9]
	v_fmac_f32_e32 v10, v51, v59
	v_fmac_f32_e32 v11, v49, v61
	v_add_f32_e32 v6, v6, v7
	v_add_f32_e32 v7, v10, v11
	s_nop 0
	v_add_f32_dpp v6, v6, v6 row_ror:8 row_mask:0xf bank_mask:0xf bound_ctrl:1
	v_add_f32_dpp v7, v7, v7 row_ror:8 row_mask:0xf bank_mask:0xf bound_ctrl:1
	s_nop 0
	v_add_f32_dpp v6, v6, v6 row_ror:4 row_mask:0xf bank_mask:0xf bound_ctrl:1
	v_add_f32_dpp v7, v7, v7 row_ror:4 row_mask:0xf bank_mask:0xf bound_ctrl:1
	s_nop 0
	v_add_f32_dpp v8, v6, v6 row_ror:2 row_mask:0xf bank_mask:0xf bound_ctrl:1
	v_add_f32_dpp v6, v7, v7 row_ror:2 row_mask:0xf bank_mask:0xf bound_ctrl:1
	s_nop 0
	v_add_f32_dpp v52, v8, v8 row_ror:1 row_mask:0xf bank_mask:0xf bound_ctrl:1
	v_mov_b32_dpp v18, v6 row_ror:1 row_mask:0xf bank_mask:0xf
	s_and_saveexec_b64 s[4:5], vcc
	s_cbranch_execz .LBB0_1244
	s_lshl_b64 s[38:39], s[20:21], 9
	v_lshl_add_u64 v[10:11], s[38:39], 2, v[42:43]
	s_waitcnt vmcnt(0)
	v_mul_f32_e32 v7, v52, v64
	v_mul_f32_e32 v19, v28, v65
	v_pk_add_f32 v[6:7], v[6:7], v[18:19]
	s_nop 0
	v_fmac_f32_e32 v6, 0x41800000, v7
	global_store_dword v[10:11], v6, off
.LBB0_1244:
	s_or_b64 exec, exec, s[4:5]
	s_add_u32 s20, s18, 0x8005
	s_addc_u32 s21, s19, 0
	s_lshl_b64 s[4:5], s[20:21], 11
	v_lshl_add_u64 v[10:11], v[46:47], 0, s[4:5]
	v_add_co_u32_e64 v6, s[4:5], s25, v10
	s_add_u32 s36, s36, 0x1800
	s_nop 0
	v_addc_co_u32_e64 v7, s[4:5], 0, v11, s[4:5]
	global_load_dwordx4 v[54:57], v[10:11], off
	global_load_dwordx4 v[58:61], v[6:7], off
	v_add_co_u32_e64 v6, s[4:5], s26, v10
	s_addc_u32 s37, s37, 0
	s_nop 0
	v_addc_co_u32_e64 v7, s[4:5], 0, v11, s[4:5]
	v_add_co_u32_e64 v12, s[4:5], s27, v10
	s_waitcnt vmcnt(4)
	v_pk_mul_f32 v[24:25], v[24:25], v[52:53] op_sel_hi:[1,0]
	v_addc_co_u32_e64 v13, s[4:5], 0, v11, s[4:5]
	v_add_co_u32_e64 v10, s[4:5], s28, v10
	global_load_dwordx4 v[6:9], v[6:7], off
	s_nop 0
	global_load_dwordx4 v[18:21], v[12:13], off
	v_addc_co_u32_e64 v11, s[4:5], 0, v11, s[4:5]
	s_add_u32 s4, s36, s12
	s_addc_u32 s5, s37, 0
	v_lshl_add_u64 v[26:27], s[4:5], 0, v[44:45]
	v_add_co_u32_e64 v26, s[4:5], s29, v26
	global_load_dwordx4 v[10:13], v[10:11], off
	s_nop 0
	v_addc_co_u32_e64 v27, s[4:5], 0, v27, s[4:5]
	global_load_dword v26, v[26:27], off
	s_lshl_b64 s[98:99], s[20:21], 7
	s_add_u32 s98, s17, s98
	s_addc_u32 s99, s35, s99
	global_load_dwordx2 v[64:65], v31, s[98:99]
	v_pk_mul_f32 v[62:63], v[22:23], v[52:53] op_sel_hi:[1,0]
	v_pk_fma_f32 v[4:5], v[48:49], v[4:5], v[24:25]
	v_pk_fma_f32 v[2:3], v[50:51], v[2:3], v[62:63]
	s_waitcnt vmcnt(6)
	v_pk_fma_f32 v[48:49], v[16:17], v[28:29], v[4:5] op_sel_hi:[1,0,1]
	v_pk_fma_f32 v[50:51], v[14:15], v[28:29], v[2:3] op_sel_hi:[1,0,1]
	v_mov_b32_e32 v3, v49
	v_mov_b32_e32 v2, v51
	v_mov_b32_e32 v22, v31
	s_waitcnt vmcnt(5)
	v_pk_mul_f32 v[4:5], v[50:51], v[54:55]
	v_pk_mul_f32 v[14:15], v[48:49], v[56:57]
	v_mov_b32_e32 v56, v55
	v_mov_b32_e32 v5, v14
	s_waitcnt vmcnt(4)
	v_mul_f32_e32 v14, v50, v58
	v_mul_f32_e32 v15, v48, v60
	v_pk_fma_f32 v[2:3], v[2:3], v[56:57], v[4:5]
	v_fmac_f32_e32 v14, v51, v59
	v_fmac_f32_e32 v15, v49, v61
	v_add_f32_e32 v2, v2, v3
	v_add_f32_e32 v3, v14, v15
	s_nop 0
	v_add_f32_dpp v2, v2, v2 row_ror:8 row_mask:0xf bank_mask:0xf bound_ctrl:1
	v_add_f32_dpp v3, v3, v3 row_ror:8 row_mask:0xf bank_mask:0xf bound_ctrl:1
	s_nop 0
	v_add_f32_dpp v2, v2, v2 row_ror:4 row_mask:0xf bank_mask:0xf bound_ctrl:1
	v_add_f32_dpp v3, v3, v3 row_ror:4 row_mask:0xf bank_mask:0xf bound_ctrl:1
	s_nop 0
	v_add_f32_dpp v4, v2, v2 row_ror:2 row_mask:0xf bank_mask:0xf bound_ctrl:1
	v_add_f32_dpp v2, v3, v3 row_ror:2 row_mask:0xf bank_mask:0xf bound_ctrl:1
	s_nop 0
	v_add_f32_dpp v52, v4, v4 row_ror:1 row_mask:0xf bank_mask:0xf bound_ctrl:1
	v_mov_b32_dpp v22, v2 row_ror:1 row_mask:0xf bank_mask:0xf
	s_and_saveexec_b64 s[4:5], vcc
	s_cbranch_execz .LBB0_1246
	s_lshl_b64 s[38:39], s[20:21], 9
	v_lshl_add_u64 v[14:15], s[38:39], 2, v[42:43]
	s_waitcnt vmcnt(0)
	v_mul_f32_e32 v3, v52, v64
	v_mul_f32_e32 v23, v26, v65
	v_pk_add_f32 v[2:3], v[2:3], v[22:23]
	s_nop 0
	v_fmac_f32_e32 v2, 0x41800000, v3
	global_store_dword v[14:15], v2, off
; #define GAS __attribute__((address_space(1)))
; DI float dot4(const f32x4& x, const f32x4& y) { return fmaf(x.y, y.y, x.x * y.x) + fmaf(x.w, y.w, x.z * y.z); }
; #define Q_POP(var, word) do { if (tid == 0) MISC[0] = __hip_atomic_fetch_add(ctl + CW_QHEAD + (word), 1u, RLX_AGENT); __syncthreads(); var = (int)MISC[0]; __syncthreads(); var = __builtin_amdgcn_readfirstlane(var); } while (0)
; #define P (*args_here())
; DI void sscan_wave(const float* SC5, const float* RKV, const float* SCAL, float* Y, const float* init, float* fin, int chain, int rg, int lane) {
;     ...
; #pragma unroll
;     for (int t = 0; t < DS; ++t) {
;         const size_t m = (size_t)MP + (size_t)b * DS + t; const float* p5 = SC5 + m * RWD + hd * 64 + 4 * j;
;         const f32x4 a4 = *(const GAS f32x4*)p5, wr4 = *(const GAS f32x4*)(p5 + ASZ), w4 = *(const GAS f32x4*)(p5 + 2 * ASZ), b4 = *(const GAS f32x4*)(p5 + 3 * ASZ), k4 = *(const GAS f32x4*)(p5 + 4 * ASZ);
;         const float vv = ((const GAS float*)RKV)[m * 1536 + 1024 + hd * 64 + row]; const f32x2 sc = *(const GAS f32x2*)(SCAL + (m * 8 + hd) * 4);
;         const float sa = rowsum16(dot4(s, a4)), y1 = rowsum16(dot4(s, wr4));
;         s = s * w4 + b4 * sa + k4 * vv;
;         if (j == 0) ((GAS float*)Y)[m * RWD + hd * 64 + row] = y1 + 16.f * (sa * sc.x + vv * sc.y);
;     }
;     *(GAS f32x4*)(fin + (size_t)chain * 4096 + (size_t)row * 64 + 4 * j) = s;
; template <int MODE, int VAR> DI void mixer_phase(const Ptrs& P, LAS unsigned char* lds, volatile LAS unsigned* MISC, gu32* ctl, int tid, int wave, int lane) {
;     ...
;     while (it < Q_PTOTAL) {
;         const int u = it - Q_PSCAN - Q_PATT;
; _Pragma("unroll 2")
;         for (int k8 = 0; k8 < 8; ++k8) { const int wt = k8 * 8 + wave; sscan_wave(SC5, RKV, SCAL, Y, P.in[4], P.out + O_WKVS, 4 * u + (wt >> 4), wt & 15, lane); }
;         Q_POP(it, 0); }
.LBB0_1246:
	s_or_b64 exec, exec, s[4:5]
	s_add_u32 s20, s18, 0x8006
	s_addc_u32 s21, s19, 0
	s_lshl_b64 s[4:5], s[20:21], 11
	v_lshl_add_u64 v[22:23], v[46:47], 0, s[4:5]
	v_add_co_u32_e64 v2, s[4:5], s25, v22
	s_add_u32 s36, s36, 0x1800
	s_nop 0
	v_addc_co_u32_e64 v3, s[4:5], 0, v23, s[4:5]
	global_load_dwordx4 v[54:57], v[22:23], off
	global_load_dwordx4 v[58:61], v[2:3], off
	v_add_co_u32_e64 v2, s[4:5], s26, v22
	s_addc_u32 s37, s37, 0
	s_nop 0
	v_addc_co_u32_e64 v3, s[4:5], 0, v23, s[4:5]
	v_add_co_u32_e64 v14, s[4:5], s27, v22
	v_mov_b32_e32 v45, v31
	s_nop 0
	v_addc_co_u32_e64 v15, s[4:5], 0, v23, s[4:5]
	v_add_co_u32_e64 v22, s[4:5], s28, v22
	global_load_dwordx4 v[2:5], v[2:3], off
	s_nop 0
	global_load_dwordx4 v[14:17], v[14:15], off
	v_addc_co_u32_e64 v23, s[4:5], 0, v23, s[4:5]
	s_add_u32 s4, s36, s12
	s_addc_u32 s5, s37, 0
	v_lshl_add_u64 v[28:29], s[4:5], 0, v[44:45]
	v_add_co_u32_e64 v28, s[4:5], s29, v28
	global_load_dwordx4 v[22:25], v[22:23], off
	s_nop 0
	v_addc_co_u32_e64 v29, s[4:5], 0, v29, s[4:5]
	global_load_dword v28, v[28:29], off
	s_lshl_b64 s[98:99], s[20:21], 7
	s_add_u32 s98, s17, s98
	s_addc_u32 s99, s35, s99
	global_load_dwordx2 v[64:65], v31, s[98:99]
	s_waitcnt vmcnt(8)
	v_pk_mul_f32 v[20:21], v[20:21], v[52:53] op_sel_hi:[1,0]
	v_pk_mul_f32 v[62:63], v[18:19], v[52:53] op_sel_hi:[1,0]
	v_pk_fma_f32 v[8:9], v[48:49], v[8:9], v[20:21]
	v_pk_fma_f32 v[6:7], v[50:51], v[6:7], v[62:63]
	s_waitcnt vmcnt(6)
	v_pk_fma_f32 v[48:49], v[12:13], v[26:27], v[8:9] op_sel_hi:[1,0,1]
	v_pk_fma_f32 v[26:27], v[10:11], v[26:27], v[6:7] op_sel_hi:[1,0,1]
	v_mov_b32_e32 v7, v49
	v_mov_b32_e32 v6, v27
	v_mov_b32_e32 v18, v31
	s_waitcnt vmcnt(5)
	v_pk_mul_f32 v[8:9], v[26:27], v[54:55]
	v_pk_mul_f32 v[10:11], v[48:49], v[56:57]
	v_mov_b32_e32 v56, v55
	v_mov_b32_e32 v9, v10
	s_waitcnt vmcnt(4)
	v_mul_f32_e32 v10, v26, v58
	v_mul_f32_e32 v11, v48, v60
	v_pk_fma_f32 v[6:7], v[6:7], v[56:57], v[8:9]
	v_fmac_f32_e32 v10, v27, v59
	v_fmac_f32_e32 v11, v49, v61
	v_add_f32_e32 v6, v6, v7
	v_add_f32_e32 v7, v10, v11
	s_nop 0
	v_add_f32_dpp v6, v6, v6 row_ror:8 row_mask:0xf bank_mask:0xf bound_ctrl:1
	v_add_f32_dpp v7, v7, v7 row_ror:8 row_mask:0xf bank_mask:0xf bound_ctrl:1
	s_nop 0
	v_add_f32_dpp v6, v6, v6 row_ror:4 row_mask:0xf bank_mask:0xf bound_ctrl:1
	v_add_f32_dpp v7, v7, v7 row_ror:4 row_mask:0xf bank_mask:0xf bound_ctrl:1
	s_nop 0
	v_add_f32_dpp v8, v6, v6 row_ror:2 row_mask:0xf bank_mask:0xf bound_ctrl:1
	v_add_f32_dpp v6, v7, v7 row_ror:2 row_mask:0xf bank_mask:0xf bound_ctrl:1
	s_nop 0
	v_add_f32_dpp v50, v8, v8 row_ror:1 row_mask:0xf bank_mask:0xf bound_ctrl:1
	v_mov_b32_dpp v18, v6 row_ror:1 row_mask:0xf bank_mask:0xf
	s_and_saveexec_b64 s[4:5], vcc
	s_cbranch_execz .LBB0_1248
	s_lshl_b64 s[38:39], s[20:21], 9
	v_lshl_add_u64 v[10:11], s[38:39], 2, v[42:43]
	s_waitcnt vmcnt(0)
	v_mul_f32_e32 v7, v50, v64
	v_mul_f32_e32 v19, v28, v65
	v_pk_add_f32 v[6:7], v[6:7], v[18:19]
	s_nop 0
	v_fmac_f32_e32 v6, 0x41800000, v7
	global_store_dword v[10:11], v6, off
.LBB0_1248:
	s_or_b64 exec, exec, s[4:5]
	s_add_u32 s18, s18, 0x8007
	s_addc_u32 s19, s19, 0
	s_lshl_b64 s[4:5], s[18:19], 11
	v_lshl_add_u64 v[10:11], v[46:47], 0, s[4:5]
	v_add_co_u32_e64 v6, s[4:5], s25, v10
	s_waitcnt vmcnt(2)
	v_pk_mul_f32 v[16:17], v[16:17], v[50:51] op_sel_hi:[1,0]
	v_addc_co_u32_e64 v7, s[4:5], 0, v11, s[4:5]
	global_load_dwordx4 v[54:57], v[10:11], off
	global_load_dwordx4 v[58:61], v[6:7], off
	v_add_co_u32_e64 v6, s[4:5], s26, v10
	v_pk_mul_f32 v[14:15], v[14:15], v[50:51] op_sel_hi:[1,0]
	s_nop 0
	v_addc_co_u32_e64 v7, s[4:5], 0, v11, s[4:5]
	v_add_co_u32_e64 v12, s[4:5], s27, v10
	v_pk_fma_f32 v[4:5], v[48:49], v[4:5], v[16:17]
	s_nop 0
	v_addc_co_u32_e64 v13, s[4:5], 0, v11, s[4:5]
	v_add_co_u32_e64 v10, s[4:5], s28, v10
	global_load_dwordx4 v[6:9], v[6:7], off
	s_nop 0
	global_load_dwordx4 v[18:21], v[12:13], off
	v_addc_co_u32_e64 v11, s[4:5], 0, v11, s[4:5]
	s_add_u32 s4, s36, s12
	s_addc_u32 s5, s37, 0
	v_lshl_add_u64 v[44:45], s[4:5], 0, v[44:45]
	v_add_co_u32_e64 v44, s[4:5], s30, v44
	global_load_dwordx4 v[10:13], v[10:11], off
	s_nop 0
	v_addc_co_u32_e64 v45, s[4:5], 0, v45, s[4:5]
	global_load_dword v44, v[44:45], off offset:2048
	s_lshl_b64 s[98:99], s[18:19], 7
	s_add_u32 s98, s17, s98
	s_addc_u32 s99, s35, s99
	global_load_dwordx2 v[64:65], v31, s[98:99]
	v_pk_fma_f32 v[14:15], v[26:27], v[2:3], v[14:15]
	s_waitcnt vmcnt(6)
	v_pk_fma_f32 v[2:3], v[24:25], v[28:29], v[4:5] op_sel_hi:[1,0,1]
	v_pk_fma_f32 v[4:5], v[22:23], v[28:29], v[14:15] op_sel_hi:[1,0,1]
	v_mov_b32_e32 v22, v31
	s_waitcnt vmcnt(5)
	v_mul_f32_e32 v14, v4, v54
	v_mul_f32_e32 v15, v2, v56
	s_waitcnt vmcnt(4)
	v_mul_f32_e32 v16, v4, v58
	v_mul_f32_e32 v17, v2, v60
	v_fmac_f32_e32 v14, v5, v55
	v_fmac_f32_e32 v15, v3, v57
	v_fmac_f32_e32 v16, v5, v59
	v_fmac_f32_e32 v17, v3, v61
	v_add_f32_e32 v14, v14, v15
	v_add_f32_e32 v15, v16, v17
	s_nop 0
	v_add_f32_dpp v14, v14, v14 row_ror:8 row_mask:0xf bank_mask:0xf bound_ctrl:1
	v_add_f32_dpp v15, v15, v15 row_ror:8 row_mask:0xf bank_mask:0xf bound_ctrl:1
	s_nop 0
	v_add_f32_dpp v14, v14, v14 row_ror:4 row_mask:0xf bank_mask:0xf bound_ctrl:1
	v_add_f32_dpp v15, v15, v15 row_ror:4 row_mask:0xf bank_mask:0xf bound_ctrl:1
	s_nop 0
	v_add_f32_dpp v14, v14, v14 row_ror:2 row_mask:0xf bank_mask:0xf bound_ctrl:1
	v_add_f32_dpp v16, v15, v15 row_ror:2 row_mask:0xf bank_mask:0xf bound_ctrl:1
	s_nop 0
	v_add_f32_dpp v14, v14, v14 row_ror:1 row_mask:0xf bank_mask:0xf bound_ctrl:1
	v_mov_b32_dpp v22, v16 row_ror:1 row_mask:0xf bank_mask:0xf
	s_and_saveexec_b64 s[4:5], vcc
	s_cbranch_execz .LBB0_1217
	s_lshl_b64 s[20:21], s[18:19], 9
	v_lshl_add_u64 v[26:27], s[20:21], 2, v[42:43]
	s_waitcnt vmcnt(0)
	v_mul_f32_e32 v17, v14, v64
	v_mul_f32_e32 v23, v44, v65
	v_pk_add_f32 v[16:17], v[16:17], v[22:23]
	s_nop 0
	v_fmac_f32_e32 v16, 0x41800000, v17
	global_store_dword v[26:27], v16, off
	s_branch .LBB0_1217

; __global__ void __launch_bounds__(NWAVES * 64, 2) mk_fwd(Args args) {
	.amdhsa_kernel _Z6mk_fwd4Args
		.amdhsa_group_segment_fixed_size 0
		.amdhsa_private_segment_fixed_size 0
		.amdhsa_kernarg_size 576
		.amdhsa_user_sgpr_count 2
		.amdhsa_user_sgpr_dispatch_ptr 0
		.amdhsa_user_sgpr_queue_ptr 0
		.amdhsa_user_sgpr_kernarg_segment_ptr 1
		.amdhsa_user_sgpr_dispatch_id 0
		.amdhsa_user_sgpr_kernarg_preload_length 0
		.amdhsa_user_sgpr_kernarg_preload_offset 0
		.amdhsa_user_sgpr_private_segment_size 0
		.amdhsa_uses_dynamic_stack 0
		.amdhsa_enable_private_segment 0
		.amdhsa_system_sgpr_workgroup_id_x 1
		.amdhsa_system_sgpr_workgroup_id_y 0
		.amdhsa_system_sgpr_workgroup_id_z 0
		.amdhsa_system_sgpr_workgroup_info 0
		.amdhsa_system_vgpr_workitem_id 0
		.amdhsa_next_free_vgpr 255
		.amdhsa_next_free_sgpr 100
		.amdhsa_accum_offset 256
		.amdhsa_reserve_vcc 1
		.amdhsa_float_round_mode_32 0
		.amdhsa_float_round_mode_16_64 0
		.amdhsa_float_denorm_mode_32 3
		.amdhsa_float_denorm_mode_16_64 3
		.amdhsa_dx10_clamp 1
		.amdhsa_ieee_mode 1
		.amdhsa_fp16_overflow 0
		.amdhsa_tg_split 0
		.amdhsa_exception_fp_ieee_invalid_op 0
		.amdhsa_exception_fp_denorm_src 0
		.amdhsa_exception_fp_ieee_div_zero 0
		.amdhsa_exception_fp_ieee_overflow 0
		.amdhsa_exception_fp_ieee_underflow 0
		.amdhsa_exception_fp_ieee_inexact 0
		.amdhsa_exception_int_div_zero 0
	.end_amdhsa_kernel

; __global__ void __launch_bounds__(NWAVES * 64, 2) mk_fwd(Args args) {
amdhsa.kernels:
  - .agpr_count:     0
    .args:
      - .offset:         0
        .size:           320
        .value_kind:     by_value
      - .offset:         320
        .size:           4
        .value_kind:     hidden_block_count_x
      - .offset:         324
        .size:           4
        .value_kind:     hidden_block_count_y
      - .offset:         328
        .size:           4
        .value_kind:     hidden_block_count_z
      - .offset:         332
        .size:           2
        .value_kind:     hidden_group_size_x
      - .offset:         334
        .size:           2
        .value_kind:     hidden_group_size_y
      - .offset:         336
        .size:           2
        .value_kind:     hidden_group_size_z
      - .offset:         338
        .size:           2
        .value_kind:     hidden_remainder_x
      - .offset:         340
        .size:           2
        .value_kind:     hidden_remainder_y
      - .offset:         342
        .size:           2
        .value_kind:     hidden_remainder_z
      - .offset:         360
        .size:           8
        .value_kind:     hidden_global_offset_x
      - .offset:         368
        .size:           8
        .value_kind:     hidden_global_offset_y
      - .offset:         376
        .size:           8
        .value_kind:     hidden_global_offset_z
      - .offset:         384
        .size:           2
        .value_kind:     hidden_grid_dims
      - .offset:         440
        .size:           4
        .value_kind:     hidden_dynamic_lds_size
    .group_segment_fixed_size: 0
    .kernarg_segment_align: 8
    .kernarg_segment_size: 576
    .language:       OpenCL C
    .language_version:
      - 2
      - 0
    .max_flat_workgroup_size: 512
    .name:           _Z6mk_fwd4Args
    .private_segment_fixed_size: 0
    .sgpr_count:     106
    .sgpr_spill_count: 62
    .symbol:         _Z6mk_fwd4Args.kd
    .uniform_work_group_size: 1
    .uses_dynamic_stack: false
    .vgpr_count:     255
    .vgpr_spill_count: 0
    .wavefront_size: 64
